# GEMM epilogue stores (MLP-up and in-proj phases) bounced through LDS so each 16-lane quarter writes 4 rows x 64 B instead of 16 rows x 16 B; plus earlier edits
# speedup vs baseline: 1.0059x; 1.0014x over previous
;     DI bool operator()(AccT& acc, const Unit& u, int wr, int wc, int fr, int fq) const {
;         const int row0 = u.pm * BM + wr * 64 + fr, col0 = u.pn * BM + wc * 32 + 8 * fq;
;         float rsv[2][4];
; #pragma unroll
;         for (int ai = 0; ai < 2; ++ai)
; #pragma unroll
;             for (int m = 0; m < 4; ++m) rsv[ai][m] = rs[row0 + ai * HALF + m * 16];
; #pragma unroll
;         for (int bj = 0; bj < 2; ++bj) {
;             const int col = col0 + bj * HALF; const bool gate = (col >= ZC_GATE) && (col < ZC_VRES); const bool s5c = col < S5W;
.LBB0_381:
	v_mbcnt_lo_u32_b32 v212, -1, 0
	v_mbcnt_hi_u32_b32 v212, -1, v212
	s_lshl_b32 s98, s90, 10
	s_add_i32 s98, s98, 0x22000
	v_lshl_add_u32 v211, v212, 4, s98
	v_and_b32_e32 v213, 15, v212
	v_lshrrev_b32_e32 v214, 4, v212
	v_lshrrev_b32_e32 v215, 2, v213
	v_lshl_add_u32 v214, v215, 4, v214
	v_and_b32_e32 v215, 3, v213
	v_lshl_add_u32 v214, v215, 2, v214
	v_lshl_add_u32 v210, v214, 4, s98
	v_lshrrev_b32_e32 v214, 4, v212
	v_bfe_u32 v215, v212, 2, 2
	v_lshl_add_u32 v215, v214, 2, v215
	v_sub_u32_e32 v215, v215, v213
	v_and_b32_e32 v213, 3, v212
	v_sub_u32_e32 v213, v213, v214
	v_lshlrev_b32_e32 v213, 4, v213
	s_movk_i32 s98, 0x5a00
	v_mad_i32_i24 v208, v215, s98, v213
	v_ashrrev_i32_e32 v209, 31, v208
	s_cmp_lt_u32 s4, 3
	s_cbranch_scc0 .Lepi_PB_noident
	v_mov_b32_e32 v210, v211
	v_mov_b32_e32 v208, 0
	v_mov_b32_e32 v209, 0

; #define GAS __attribute__((address_space(1)))
; DI unsigned pk2(float lo, float hi) { f32x2 v = {lo, hi}; bf16x2_t r = __builtin_convertvector(v, bf16x2_t); return __builtin_bit_cast(unsigned, r); }
; DI float sigmoidf_(float x) { return __builtin_amdgcn_rcpf(1.f + __expf(-x)); }
;     DI bool operator()(AccT& acc, const Unit& u, int wr, int wc, int fr, int fq) const {
;     ...
;         for (int bj = 0; bj < 2; ++bj) {
;             const int col = col0 + bj * HALF; const bool gate = (col >= ZC_GATE) && (col < ZC_VRES); const bool s5c = col < S5W;
;             f32x4 b0 = {0.f, 0.f, 0.f, 0.f}, b1 = b0;
;             if (gate) { b0 = *(const GAS f32x4*)(gbias + (col - ZC_GATE)); b1 = *(const GAS f32x4*)(gbias + (col - ZC_GATE) + 4); }
; #pragma unroll
;             for (int ai = 0; ai < 2; ++ai)
; #pragma unroll
;                 for (int m = 0; m < 4; ++m) {
;                     f32x4 v0 = acc[ai][bj][m][0] * rsv[ai][m], v1 = acc[ai][bj][m][1] * rsv[ai][m];
;                     if (gate) { v0 += b0; v1 += b1;
; #pragma unroll
;                         for (int e = 0; e < 4; ++e) { v0[e] = sigmoidf_(v0[e]); v1[e] = sigmoidf_(v1[e]); } }
;                     u32x4 w; w.x = pk2(v0[0], v0[1]); w.y = pk2(v0[2], v0[3]); w.z = pk2(v1[0], v1[1]); w.w = pk2(v1[2], v1[3]);
;                     if (s5c) *(GAS u32x4*)(ZS5 + ((size_t)(col >> 4) * M + (row0 + ai * HALF + m * 16)) * 16 + (col & 8)) = w;
;                     else *(GAS u32x4*)(Z + (size_t)(row0 + ai * HALF + m * 16) * ZP + col) = w;
;                 }
.LBB0_385:
	s_or_b64 exec, exec, s[16:17]
	s_movk_i32 s0, 0x2ff
	v_cmp_lt_i32_e32 vcc, s0, v184
	v_ashrrev_i32_e32 v159, 31, v158
	s_and_saveexec_b64 s[0:1], vcc
	s_xor_b64 s[0:1], exec, s[0:1]
	v_mov_b64_e32 v[128:129], s[6:7]
	s_movk_i32 s16, 0x5a00
	v_mad_i64_i32 v[128:129], s[16:17], v158, s16, v[128:129]
	v_lshl_add_u64 v[168:169], v[184:185], 1, v[128:129]
	s_or_saveexec_b64 s[0:1], s[0:1]
	v_ashrrev_i32_e32 v128, 4, v184
	v_ashrrev_i32_e32 v129, 31, v128
	v_lshlrev_b64 v[128:129], 19, v[128:129]
	v_lshl_add_u64 v[132:133], s[10:11], 0, v[128:129]
	v_lshlrev_b64 v[130:131], 5, v[158:159]
	v_lshlrev_b32_e32 v128, 1, v144
	s_xor_b64 exec, exec, s[0:1]
	v_lshl_add_u64 v[168:169], v[132:133], 0, v[130:131]
	v_mov_b32_e32 v129, v185
	v_lshl_add_u64 v[168:169], v[168:169], 0, v[128:129]
	s_or_b64 exec, exec, s[0:1]
	v_cvt_pk_bf16_f32 v175, v164, v165
	v_mov_b32_e32 v164, v157
	v_cvt_pk_bf16_f32 v174, v134, v135
	v_cvt_pk_bf16_f32 v176, v162, v163
	v_cvt_pk_bf16_f32 v177, v166, v167
	v_pk_mul_f32 v[134:135], v[126:127], v[164:165] op_sel_hi:[1,0]
	v_pk_mul_f32 v[124:125], v[124:125], v[164:165] op_sel_hi:[1,0]
	v_pk_mul_f32 v[162:163], v[122:123], v[164:165] op_sel_hi:[1,0]
	v_pk_mul_f32 v[126:127], v[120:121], v[164:165] op_sel_hi:[1,0]
	v_lshl_add_u64 v[204:205], v[168:169], 0, v[208:209]
	ds_write_b128 v210, v[174:177]
	ds_read_b128 v[178:181], v211
	s_and_saveexec_b64 s[0:1], s[4:5]
	s_xor_b64 s[0:1], exec, s[0:1]
	s_andn2_saveexec_b64 s[16:17], s[0:1]
	s_cbranch_execz .LBB0_391
	s_waitcnt vmcnt(0)
	v_pk_add_f32 v[122:123], v[124:125], v[104:105]
	v_pk_add_f32 v[124:125], v[126:127], v[108:109]
	v_mul_f32_e32 v122, 0xbfb8aa3b, v122
	v_exp_f32_e32 v122, v122
	v_mul_f32_e32 v124, 0xbfb8aa3b, v124
	v_exp_f32_e32 v126, v124
	v_mul_f32_e32 v123, 0xbfb8aa3b, v123
	v_exp_f32_e32 v123, v123
	v_mul_f32_e32 v125, 0xbfb8aa3b, v125
	v_exp_f32_e32 v127, v125
	v_pk_add_f32 v[120:121], v[134:135], v[106:107]
	v_add_f32_e32 v122, 1.0, v122
	v_pk_add_f32 v[134:135], v[162:163], v[110:111]
	v_rcp_f32_e32 v124, v122
	v_add_f32_e32 v122, 1.0, v126
	v_mul_f32_e32 v120, 0xbfb8aa3b, v120
	v_rcp_f32_e32 v126, v122
	v_add_f32_e32 v122, 1.0, v123
	v_exp_f32_e32 v120, v120
	v_mul_f32_e32 v123, 0xbfb8aa3b, v134
	v_rcp_f32_e32 v125, v122
	v_add_f32_e32 v122, 1.0, v127
	v_exp_f32_e32 v123, v123
	v_mul_f32_e32 v121, 0xbfb8aa3b, v121
	v_rcp_f32_e32 v127, v122
	v_exp_f32_e32 v121, v121
	v_mul_f32_e32 v122, 0xbfb8aa3b, v135
	v_exp_f32_e32 v122, v122
	v_add_f32_e32 v120, 1.0, v120
	v_rcp_f32_e32 v134, v120
	v_add_f32_e32 v120, 1.0, v123
	v_rcp_f32_e32 v162, v120
	v_add_f32_e32 v120, 1.0, v121
	v_rcp_f32_e32 v135, v120
	v_add_f32_e32 v120, 1.0, v122
	v_rcp_f32_e32 v163, v120
.LBB0_391:
	s_or_b64 exec, exec, s[16:17]
	v_or_b32_e32 v120, 16, v158
	v_ashrrev_i32_e32 v121, 31, v120
	s_and_saveexec_b64 s[0:1], vcc
	s_xor_b64 s[0:1], exec, s[0:1]
	v_mov_b64_e32 v[122:123], s[6:7]
	s_movk_i32 s16, 0x5a00
	v_mad_i64_i32 v[122:123], s[16:17], v120, s16, v[122:123]
	v_lshl_add_u64 v[164:165], v[184:185], 1, v[122:123]
	s_or_saveexec_b64 s[0:1], s[0:1]
	v_lshlrev_b64 v[122:123], 5, v[120:121]
	s_xor_b64 exec, exec, s[0:1]
	v_lshl_add_u64 v[164:165], v[132:133], 0, v[122:123]
	v_mov_b32_e32 v129, v185
	v_lshl_add_u64 v[164:165], v[164:165], 0, v[128:129]
	s_or_b64 exec, exec, s[0:1]
	v_cvt_pk_bf16_f32 v124, v124, v125
	v_cvt_pk_bf16_f32 v125, v134, v135
	v_cvt_pk_bf16_f32 v126, v126, v127
	v_cvt_pk_bf16_f32 v127, v162, v163
	v_lshl_add_u64 v[206:207], v[164:165], 0, v[208:209]
	ds_write_b128 v210, v[124:127]
	ds_read_b128 v[200:203], v211
	s_waitcnt lgkmcnt(2)
	global_store_dwordx4 v[204:205], v[178:181], off
	v_pk_mul_f32 v[116:117], v[116:117], v[154:155] op_sel_hi:[1,0]
	s_nop 0
	v_pk_mul_f32 v[124:125], v[118:119], v[154:155] op_sel_hi:[1,0]
	v_pk_mul_f32 v[126:127], v[114:115], v[154:155] op_sel_hi:[1,0]
	v_pk_mul_f32 v[118:119], v[112:113], v[154:155] op_sel_hi:[1,0]
	s_and_saveexec_b64 s[0:1], s[4:5]
	s_xor_b64 s[0:1], exec, s[0:1]
	s_andn2_saveexec_b64 s[16:17], s[0:1]
	s_cbranch_execz .LBB0_397
	s_waitcnt vmcnt(0)
	v_pk_add_f32 v[114:115], v[116:117], v[104:105]
	v_pk_add_f32 v[116:117], v[118:119], v[108:109]
	v_mul_f32_e32 v114, 0xbfb8aa3b, v114
	v_exp_f32_e32 v114, v114
	v_mul_f32_e32 v116, 0xbfb8aa3b, v116
	v_exp_f32_e32 v118, v116
	v_mul_f32_e32 v115, 0xbfb8aa3b, v115
	v_exp_f32_e32 v115, v115
	v_mul_f32_e32 v117, 0xbfb8aa3b, v117
	v_exp_f32_e32 v119, v117
	v_pk_add_f32 v[112:113], v[124:125], v[106:107]
	v_add_f32_e32 v114, 1.0, v114
	v_pk_add_f32 v[124:125], v[126:127], v[110:111]
	v_rcp_f32_e32 v116, v114
	v_add_f32_e32 v114, 1.0, v118
	v_mul_f32_e32 v112, 0xbfb8aa3b, v112
	v_rcp_f32_e32 v118, v114
	v_add_f32_e32 v114, 1.0, v115
	v_exp_f32_e32 v112, v112
	v_mul_f32_e32 v115, 0xbfb8aa3b, v124
	v_rcp_f32_e32 v117, v114
	v_add_f32_e32 v114, 1.0, v119
	v_exp_f32_e32 v115, v115
	v_mul_f32_e32 v113, 0xbfb8aa3b, v113
	v_rcp_f32_e32 v119, v114
	v_exp_f32_e32 v113, v113
	v_mul_f32_e32 v114, 0xbfb8aa3b, v125
	v_exp_f32_e32 v114, v114
	v_add_f32_e32 v112, 1.0, v112
	v_rcp_f32_e32 v124, v112
	v_add_f32_e32 v112, 1.0, v115
	v_rcp_f32_e32 v126, v112
	v_add_f32_e32 v112, 1.0, v113
	v_rcp_f32_e32 v125, v112
	v_add_f32_e32 v112, 1.0, v114
	v_rcp_f32_e32 v127, v112
; #define GAS __attribute__((address_space(1)))
; DI unsigned pk2(float lo, float hi) { f32x2 v = {lo, hi}; bf16x2_t r = __builtin_convertvector(v, bf16x2_t); return __builtin_bit_cast(unsigned, r); }
; DI float sigmoidf_(float x) { return __builtin_amdgcn_rcpf(1.f + __expf(-x)); }
;     DI bool operator()(AccT& acc, const Unit& u, int wr, int wc, int fr, int fq) const {
;     ...
;         for (int bj = 0; bj < 2; ++bj) {
;             const int col = col0 + bj * HALF; const bool gate = (col >= ZC_GATE) && (col < ZC_VRES); const bool s5c = col < S5W;
;             f32x4 b0 = {0.f, 0.f, 0.f, 0.f}, b1 = b0;
;             if (gate) { b0 = *(const GAS f32x4*)(gbias + (col - ZC_GATE)); b1 = *(const GAS f32x4*)(gbias + (col - ZC_GATE) + 4); }
; #pragma unroll
;             for (int ai = 0; ai < 2; ++ai)
; #pragma unroll
;                 for (int m = 0; m < 4; ++m) {
;                     f32x4 v0 = acc[ai][bj][m][0] * rsv[ai][m], v1 = acc[ai][bj][m][1] * rsv[ai][m];
;                     if (gate) { v0 += b0; v1 += b1;
; #pragma unroll
;                         for (int e = 0; e < 4; ++e) { v0[e] = sigmoidf_(v0[e]); v1[e] = sigmoidf_(v1[e]); } }
;                     u32x4 w; w.x = pk2(v0[0], v0[1]); w.y = pk2(v0[2], v0[3]); w.z = pk2(v1[0], v1[1]); w.w = pk2(v1[2], v1[3]);
;                     if (s5c) *(GAS u32x4*)(ZS5 + ((size_t)(col >> 4) * M + (row0 + ai * HALF + m * 16)) * 16 + (col & 8)) = w;
;                     else *(GAS u32x4*)(Z + (size_t)(row0 + ai * HALF + m * 16) * ZP + col) = w;
;                 }
.LBB0_397:
	s_or_b64 exec, exec, s[16:17]
	v_or_b32_e32 v112, 32, v158
	v_ashrrev_i32_e32 v113, 31, v112
	s_and_saveexec_b64 s[0:1], vcc
	s_xor_b64 s[0:1], exec, s[0:1]
	v_mov_b64_e32 v[114:115], s[6:7]
	s_movk_i32 s16, 0x5a00
	v_mad_i64_i32 v[114:115], s[16:17], v112, s16, v[114:115]
	v_lshl_add_u64 v[134:135], v[184:185], 1, v[114:115]
	s_or_saveexec_b64 s[0:1], s[0:1]
	v_lshlrev_b64 v[114:115], 5, v[112:113]
	s_xor_b64 exec, exec, s[0:1]
	v_lshl_add_u64 v[134:135], v[132:133], 0, v[114:115]
	v_mov_b32_e32 v129, v185
	v_lshl_add_u64 v[134:135], v[134:135], 0, v[128:129]
	s_or_b64 exec, exec, s[0:1]
	v_cvt_pk_bf16_f32 v116, v116, v117
	v_cvt_pk_bf16_f32 v117, v124, v125
	v_cvt_pk_bf16_f32 v118, v118, v119
	v_cvt_pk_bf16_f32 v119, v126, v127
	v_mov_b32_e32 v124, v155
	v_lshl_add_u64 v[204:205], v[134:135], 0, v[208:209]
	ds_write_b128 v210, v[116:119]
	ds_read_b128 v[178:181], v211
	s_waitcnt lgkmcnt(2)
	global_store_dwordx4 v[206:207], v[200:203], off
	v_pk_mul_f32 v[100:101], v[100:101], v[124:125] op_sel_hi:[1,0]
	s_nop 0
	v_pk_mul_f32 v[116:117], v[102:103], v[124:125] op_sel_hi:[1,0]
	v_pk_mul_f32 v[118:119], v[98:99], v[124:125] op_sel_hi:[1,0]
	v_pk_mul_f32 v[102:103], v[96:97], v[124:125] op_sel_hi:[1,0]
	s_and_saveexec_b64 s[0:1], s[4:5]
	s_xor_b64 s[0:1], exec, s[0:1]
	s_andn2_saveexec_b64 s[16:17], s[0:1]
	s_cbranch_execz .LBB0_403
	s_waitcnt vmcnt(0)
	v_pk_add_f32 v[98:99], v[100:101], v[104:105]
	v_pk_add_f32 v[100:101], v[102:103], v[108:109]
	v_mul_f32_e32 v98, 0xbfb8aa3b, v98
	v_exp_f32_e32 v98, v98
	v_mul_f32_e32 v100, 0xbfb8aa3b, v100
	v_exp_f32_e32 v102, v100
	v_mul_f32_e32 v99, 0xbfb8aa3b, v99
	v_exp_f32_e32 v99, v99
	v_mul_f32_e32 v101, 0xbfb8aa3b, v101
	v_exp_f32_e32 v103, v101
	v_pk_add_f32 v[96:97], v[116:117], v[106:107]
	v_add_f32_e32 v98, 1.0, v98
	v_pk_add_f32 v[116:117], v[118:119], v[110:111]
	v_rcp_f32_e32 v100, v98
	v_add_f32_e32 v98, 1.0, v102
	v_mul_f32_e32 v96, 0xbfb8aa3b, v96
	v_rcp_f32_e32 v102, v98
	v_add_f32_e32 v98, 1.0, v99
	v_exp_f32_e32 v96, v96
	v_mul_f32_e32 v99, 0xbfb8aa3b, v116
	v_rcp_f32_e32 v101, v98
	v_add_f32_e32 v98, 1.0, v103
	v_exp_f32_e32 v99, v99
	v_mul_f32_e32 v97, 0xbfb8aa3b, v97
	v_rcp_f32_e32 v103, v98
	v_exp_f32_e32 v97, v97
	v_mul_f32_e32 v98, 0xbfb8aa3b, v117
	v_exp_f32_e32 v98, v98
	v_add_f32_e32 v96, 1.0, v96
	v_rcp_f32_e32 v116, v96
	v_add_f32_e32 v96, 1.0, v99
	v_rcp_f32_e32 v118, v96
	v_add_f32_e32 v96, 1.0, v97
	v_rcp_f32_e32 v117, v96
	v_add_f32_e32 v96, 1.0, v98
	v_rcp_f32_e32 v119, v96
.LBB0_403:
	s_or_b64 exec, exec, s[16:17]
	v_or_b32_e32 v96, 48, v158
	v_ashrrev_i32_e32 v97, 31, v96
	s_and_saveexec_b64 s[0:1], vcc
	s_xor_b64 s[0:1], exec, s[0:1]
	v_mov_b64_e32 v[98:99], s[6:7]
	s_movk_i32 s16, 0x5a00
	v_mad_i64_i32 v[98:99], s[16:17], v96, s16, v[98:99]
	v_lshl_add_u64 v[124:125], v[184:185], 1, v[98:99]
	s_or_saveexec_b64 s[0:1], s[0:1]
	v_lshlrev_b64 v[98:99], 5, v[96:97]
	s_xor_b64 exec, exec, s[0:1]
	v_lshl_add_u64 v[124:125], v[132:133], 0, v[98:99]
	v_mov_b32_e32 v129, v185
	v_lshl_add_u64 v[124:125], v[124:125], 0, v[128:129]
	s_or_b64 exec, exec, s[0:1]
	v_cvt_pk_bf16_f32 v100, v100, v101
	v_cvt_pk_bf16_f32 v101, v116, v117
	v_cvt_pk_bf16_f32 v102, v102, v103
	v_cvt_pk_bf16_f32 v103, v118, v119
	v_lshl_add_u64 v[206:207], v[124:125], 0, v[208:209]
	ds_write_b128 v210, v[100:103]
	ds_read_b128 v[200:203], v211
	s_waitcnt lgkmcnt(2)
	global_store_dwordx4 v[204:205], v[178:181], off
	v_pk_mul_f32 v[92:93], v[92:93], v[152:153] op_sel_hi:[1,0]
	s_nop 0
	v_pk_mul_f32 v[100:101], v[94:95], v[152:153] op_sel_hi:[1,0]
	v_pk_mul_f32 v[102:103], v[90:91], v[152:153] op_sel_hi:[1,0]
	v_pk_mul_f32 v[94:95], v[88:89], v[152:153] op_sel_hi:[1,0]
	s_and_saveexec_b64 s[0:1], s[4:5]
	s_xor_b64 s[0:1], exec, s[0:1]
	s_andn2_saveexec_b64 s[16:17], s[0:1]
	s_cbranch_execz .LBB0_409
	s_waitcnt vmcnt(0)
	v_pk_add_f32 v[90:91], v[92:93], v[104:105]
	v_pk_add_f32 v[92:93], v[94:95], v[108:109]
	v_mul_f32_e32 v90, 0xbfb8aa3b, v90
	v_exp_f32_e32 v90, v90
	v_mul_f32_e32 v92, 0xbfb8aa3b, v92
	v_exp_f32_e32 v94, v92
	v_mul_f32_e32 v91, 0xbfb8aa3b, v91
	v_exp_f32_e32 v91, v91
	v_mul_f32_e32 v93, 0xbfb8aa3b, v93
	v_exp_f32_e32 v95, v93
	v_pk_add_f32 v[88:89], v[100:101], v[106:107]
	v_add_f32_e32 v90, 1.0, v90
	v_pk_add_f32 v[100:101], v[102:103], v[110:111]
	v_rcp_f32_e32 v92, v90
	v_add_f32_e32 v90, 1.0, v94
	v_mul_f32_e32 v88, 0xbfb8aa3b, v88
	v_rcp_f32_e32 v94, v90
	v_add_f32_e32 v90, 1.0, v91
	v_exp_f32_e32 v88, v88
	v_mul_f32_e32 v91, 0xbfb8aa3b, v100
	v_rcp_f32_e32 v93, v90
	v_add_f32_e32 v90, 1.0, v95
	v_exp_f32_e32 v91, v91
	v_mul_f32_e32 v89, 0xbfb8aa3b, v89
	v_rcp_f32_e32 v95, v90
	v_exp_f32_e32 v89, v89
	v_mul_f32_e32 v90, 0xbfb8aa3b, v101
	v_exp_f32_e32 v90, v90
	v_add_f32_e32 v88, 1.0, v88
	v_rcp_f32_e32 v100, v88
	v_add_f32_e32 v88, 1.0, v91
	v_rcp_f32_e32 v102, v88
	v_add_f32_e32 v88, 1.0, v89
	v_rcp_f32_e32 v101, v88
	v_add_f32_e32 v88, 1.0, v90
	v_rcp_f32_e32 v103, v88
; #define GAS __attribute__((address_space(1)))
; DI unsigned pk2(float lo, float hi) { f32x2 v = {lo, hi}; bf16x2_t r = __builtin_convertvector(v, bf16x2_t); return __builtin_bit_cast(unsigned, r); }
; DI float sigmoidf_(float x) { return __builtin_amdgcn_rcpf(1.f + __expf(-x)); }
;     DI bool operator()(AccT& acc, const Unit& u, int wr, int wc, int fr, int fq) const {
;     ...
;         for (int bj = 0; bj < 2; ++bj) {
;             const int col = col0 + bj * HALF; const bool gate = (col >= ZC_GATE) && (col < ZC_VRES); const bool s5c = col < S5W;
;             f32x4 b0 = {0.f, 0.f, 0.f, 0.f}, b1 = b0;
;             if (gate) { b0 = *(const GAS f32x4*)(gbias + (col - ZC_GATE)); b1 = *(const GAS f32x4*)(gbias + (col - ZC_GATE) + 4); }
; #pragma unroll
;             for (int ai = 0; ai < 2; ++ai)
; #pragma unroll
;                 for (int m = 0; m < 4; ++m) {
;                     f32x4 v0 = acc[ai][bj][m][0] * rsv[ai][m], v1 = acc[ai][bj][m][1] * rsv[ai][m];
;                     if (gate) { v0 += b0; v1 += b1;
; #pragma unroll
;                         for (int e = 0; e < 4; ++e) { v0[e] = sigmoidf_(v0[e]); v1[e] = sigmoidf_(v1[e]); } }
;                     u32x4 w; w.x = pk2(v0[0], v0[1]); w.y = pk2(v0[2], v0[3]); w.z = pk2(v1[0], v1[1]); w.w = pk2(v1[2], v1[3]);
;                     if (s5c) *(GAS u32x4*)(ZS5 + ((size_t)(col >> 4) * M + (row0 + ai * HALF + m * 16)) * 16 + (col & 8)) = w;
;                     else *(GAS u32x4*)(Z + (size_t)(row0 + ai * HALF + m * 16) * ZP + col) = w;
;                 }
.LBB0_409:
	s_or_b64 exec, exec, s[16:17]
	v_add_u32_e32 v88, 0x80, v158
	v_ashrrev_i32_e32 v89, 31, v88
	s_and_saveexec_b64 s[0:1], vcc
	s_xor_b64 s[0:1], exec, s[0:1]
	v_mov_b64_e32 v[90:91], s[6:7]
	s_movk_i32 s16, 0x5a00
	v_mad_i64_i32 v[90:91], s[16:17], v88, s16, v[90:91]
	v_lshl_add_u64 v[116:117], v[184:185], 1, v[90:91]
	s_or_saveexec_b64 s[0:1], s[0:1]
	v_lshlrev_b64 v[90:91], 5, v[88:89]
	s_xor_b64 exec, exec, s[0:1]
	v_lshl_add_u64 v[116:117], v[132:133], 0, v[90:91]
	v_mov_b32_e32 v129, v185
	v_lshl_add_u64 v[116:117], v[116:117], 0, v[128:129]
	s_or_b64 exec, exec, s[0:1]
	v_cvt_pk_bf16_f32 v92, v92, v93
	v_cvt_pk_bf16_f32 v93, v100, v101
	v_cvt_pk_bf16_f32 v94, v94, v95
	v_cvt_pk_bf16_f32 v95, v102, v103
	v_mov_b32_e32 v100, v153
	v_lshl_add_u64 v[204:205], v[116:117], 0, v[208:209]
	ds_write_b128 v210, v[92:95]
	ds_read_b128 v[178:181], v211
	s_waitcnt lgkmcnt(2)
	global_store_dwordx4 v[206:207], v[200:203], off
	v_pk_mul_f32 v[84:85], v[84:85], v[100:101] op_sel_hi:[1,0]
	s_nop 0
	v_pk_mul_f32 v[92:93], v[86:87], v[100:101] op_sel_hi:[1,0]
	v_pk_mul_f32 v[94:95], v[82:83], v[100:101] op_sel_hi:[1,0]
	v_pk_mul_f32 v[86:87], v[80:81], v[100:101] op_sel_hi:[1,0]
	s_and_saveexec_b64 s[0:1], s[4:5]
	s_xor_b64 s[0:1], exec, s[0:1]
	s_andn2_saveexec_b64 s[16:17], s[0:1]
	s_cbranch_execz .LBB0_415
	s_waitcnt vmcnt(0)
	v_pk_add_f32 v[82:83], v[84:85], v[104:105]
	v_pk_add_f32 v[84:85], v[86:87], v[108:109]
	v_mul_f32_e32 v82, 0xbfb8aa3b, v82
	v_exp_f32_e32 v82, v82
	v_mul_f32_e32 v84, 0xbfb8aa3b, v84
	v_exp_f32_e32 v86, v84
	v_mul_f32_e32 v83, 0xbfb8aa3b, v83
	v_exp_f32_e32 v83, v83
	v_mul_f32_e32 v85, 0xbfb8aa3b, v85
	v_exp_f32_e32 v87, v85
	v_pk_add_f32 v[80:81], v[92:93], v[106:107]
	v_add_f32_e32 v82, 1.0, v82
	v_pk_add_f32 v[92:93], v[94:95], v[110:111]
	v_rcp_f32_e32 v84, v82
	v_add_f32_e32 v82, 1.0, v86
	v_mul_f32_e32 v80, 0xbfb8aa3b, v80
	v_rcp_f32_e32 v86, v82
	v_add_f32_e32 v82, 1.0, v83
	v_exp_f32_e32 v80, v80
	v_mul_f32_e32 v83, 0xbfb8aa3b, v92
	v_rcp_f32_e32 v85, v82
	v_add_f32_e32 v82, 1.0, v87
	v_exp_f32_e32 v83, v83
	v_mul_f32_e32 v81, 0xbfb8aa3b, v81
	v_rcp_f32_e32 v87, v82
	v_exp_f32_e32 v81, v81
	v_mul_f32_e32 v82, 0xbfb8aa3b, v93
	v_exp_f32_e32 v82, v82
	v_add_f32_e32 v80, 1.0, v80
	v_rcp_f32_e32 v92, v80
	v_add_f32_e32 v80, 1.0, v83
	v_rcp_f32_e32 v94, v80
	v_add_f32_e32 v80, 1.0, v81
	v_rcp_f32_e32 v93, v80
	v_add_f32_e32 v80, 1.0, v82
	v_rcp_f32_e32 v95, v80
.LBB0_415:
	s_or_b64 exec, exec, s[16:17]
	v_add_u32_e32 v80, 0x90, v158
	v_ashrrev_i32_e32 v81, 31, v80
	s_and_saveexec_b64 s[0:1], vcc
	s_xor_b64 s[0:1], exec, s[0:1]
	v_mov_b64_e32 v[82:83], s[6:7]
	s_movk_i32 s16, 0x5a00
	v_mad_i64_i32 v[82:83], s[16:17], v80, s16, v[82:83]
	v_lshl_add_u64 v[100:101], v[184:185], 1, v[82:83]
	s_or_saveexec_b64 s[0:1], s[0:1]
	v_lshlrev_b64 v[82:83], 5, v[80:81]
	s_xor_b64 exec, exec, s[0:1]
	v_lshl_add_u64 v[100:101], v[132:133], 0, v[82:83]
	v_mov_b32_e32 v129, v185
	v_lshl_add_u64 v[100:101], v[100:101], 0, v[128:129]
	s_or_b64 exec, exec, s[0:1]
	v_cvt_pk_bf16_f32 v84, v84, v85
	v_cvt_pk_bf16_f32 v85, v92, v93
	v_cvt_pk_bf16_f32 v86, v86, v87
	v_cvt_pk_bf16_f32 v87, v94, v95
	v_lshl_add_u64 v[206:207], v[100:101], 0, v[208:209]
	ds_write_b128 v210, v[84:87]
	ds_read_b128 v[200:203], v211
	s_waitcnt lgkmcnt(2)
	global_store_dwordx4 v[204:205], v[178:181], off
	v_pk_mul_f32 v[76:77], v[76:77], v[150:151] op_sel_hi:[1,0]
	v_pk_mul_f32 v[72:73], v[72:73], v[150:151] op_sel_hi:[1,0]
	v_pk_mul_f32 v[84:85], v[78:79], v[150:151] op_sel_hi:[1,0]
	v_pk_mul_f32 v[86:87], v[74:75], v[150:151] op_sel_hi:[1,0]
	s_and_saveexec_b64 s[0:1], s[4:5]
	s_xor_b64 s[0:1], exec, s[0:1]
	s_andn2_saveexec_b64 s[16:17], s[0:1]
	s_cbranch_execz .LBB0_421
	s_waitcnt vmcnt(0)
	v_pk_add_f32 v[74:75], v[84:85], v[106:107]
	v_pk_add_f32 v[78:79], v[86:87], v[110:111]
	v_mul_f32_e32 v74, 0xbfb8aa3b, v74
	v_exp_f32_e32 v74, v74
	v_mul_f32_e32 v78, 0xbfb8aa3b, v78
	v_exp_f32_e32 v78, v78
	v_pk_add_f32 v[76:77], v[76:77], v[104:105]
	v_pk_add_f32 v[72:73], v[72:73], v[108:109]
	v_add_f32_e32 v74, 1.0, v74
	v_mul_f32_e32 v75, 0xbfb8aa3b, v75
	v_mul_f32_e32 v76, 0xbfb8aa3b, v76
	v_mul_f32_e32 v72, 0xbfb8aa3b, v72
	v_mul_f32_e32 v77, 0xbfb8aa3b, v77
	v_mul_f32_e32 v73, 0xbfb8aa3b, v73
	v_rcp_f32_e32 v84, v74
	v_add_f32_e32 v74, 1.0, v78
	v_exp_f32_e32 v75, v75
	v_mul_f32_e32 v78, 0xbfb8aa3b, v79
	v_exp_f32_e32 v76, v76
	v_exp_f32_e32 v72, v72
	v_exp_f32_e32 v77, v77
	v_exp_f32_e32 v73, v73
	v_exp_f32_e32 v78, v78
	v_rcp_f32_e32 v86, v74
	v_add_f32_e32 v74, 1.0, v75
	v_add_f32_e32 v76, 1.0, v76
	v_add_f32_e32 v72, 1.0, v72
	v_add_f32_e32 v77, 1.0, v77
	v_add_f32_e32 v73, 1.0, v73
	v_rcp_f32_e32 v85, v74
	v_add_f32_e32 v74, 1.0, v78
	v_rcp_f32_e32 v76, v76
	v_rcp_f32_e32 v72, v72
	v_rcp_f32_e32 v77, v77
	v_rcp_f32_e32 v73, v73
	v_rcp_f32_e32 v87, v74
; #define GAS __attribute__((address_space(1)))
; DI unsigned pk2(float lo, float hi) { f32x2 v = {lo, hi}; bf16x2_t r = __builtin_convertvector(v, bf16x2_t); return __builtin_bit_cast(unsigned, r); }
; DI float sigmoidf_(float x) { return __builtin_amdgcn_rcpf(1.f + __expf(-x)); }
;     DI bool operator()(AccT& acc, const Unit& u, int wr, int wc, int fr, int fq) const {
;     ...
;         for (int bj = 0; bj < 2; ++bj) {
;             const int col = col0 + bj * HALF; const bool gate = (col >= ZC_GATE) && (col < ZC_VRES); const bool s5c = col < S5W;
;             f32x4 b0 = {0.f, 0.f, 0.f, 0.f}, b1 = b0;
;             if (gate) { b0 = *(const GAS f32x4*)(gbias + (col - ZC_GATE)); b1 = *(const GAS f32x4*)(gbias + (col - ZC_GATE) + 4); }
; #pragma unroll
;             for (int ai = 0; ai < 2; ++ai)
; #pragma unroll
;                 for (int m = 0; m < 4; ++m) {
;                     f32x4 v0 = acc[ai][bj][m][0] * rsv[ai][m], v1 = acc[ai][bj][m][1] * rsv[ai][m];
;                     if (gate) { v0 += b0; v1 += b1;
; #pragma unroll
;                         for (int e = 0; e < 4; ++e) { v0[e] = sigmoidf_(v0[e]); v1[e] = sigmoidf_(v1[e]); } }
;                     u32x4 w; w.x = pk2(v0[0], v0[1]); w.y = pk2(v0[2], v0[3]); w.z = pk2(v1[0], v1[1]); w.w = pk2(v1[2], v1[3]);
;                     if (s5c) *(GAS u32x4*)(ZS5 + ((size_t)(col >> 4) * M + (row0 + ai * HALF + m * 16)) * 16 + (col & 8)) = w;
;                     else *(GAS u32x4*)(Z + (size_t)(row0 + ai * HALF + m * 16) * ZP + col) = w;
;                 }
.LBB0_421:
	s_or_b64 exec, exec, s[16:17]
	v_add_u32_e32 v74, 0xa0, v158
	v_ashrrev_i32_e32 v75, 31, v74
	s_and_saveexec_b64 s[0:1], vcc
	s_xor_b64 s[0:1], exec, s[0:1]
	v_mov_b64_e32 v[78:79], s[6:7]
	s_movk_i32 s16, 0x5a00
	v_mad_i64_i32 v[78:79], s[16:17], v74, s16, v[78:79]
	v_lshl_add_u64 v[92:93], v[184:185], 1, v[78:79]
	s_or_saveexec_b64 s[0:1], s[0:1]
	v_lshlrev_b64 v[78:79], 5, v[74:75]
	s_xor_b64 exec, exec, s[0:1]
	v_lshl_add_u64 v[92:93], v[132:133], 0, v[78:79]
	v_mov_b32_e32 v129, v185
	v_lshl_add_u64 v[92:93], v[92:93], 0, v[128:129]
	s_or_b64 exec, exec, s[0:1]
	v_cvt_pk_bf16_f32 v102, v72, v73
	v_mov_b32_e32 v72, v151
	v_cvt_pk_bf16_f32 v100, v76, v77
	v_cvt_pk_bf16_f32 v101, v84, v85
	v_cvt_pk_bf16_f32 v103, v86, v87
	v_pk_mul_f32 v[70:71], v[70:71], v[72:73] op_sel_hi:[1,0]
	v_pk_mul_f32 v[68:69], v[68:69], v[72:73] op_sel_hi:[1,0]
	v_pk_mul_f32 v[66:67], v[66:67], v[72:73] op_sel_hi:[1,0]
	v_pk_mul_f32 v[64:65], v[64:65], v[72:73] op_sel_hi:[1,0]
	v_lshl_add_u64 v[204:205], v[92:93], 0, v[208:209]
	ds_write_b128 v210, v[100:103]
	ds_read_b128 v[178:181], v211
	s_waitcnt lgkmcnt(2)
	global_store_dwordx4 v[206:207], v[200:203], off
	s_and_saveexec_b64 s[0:1], s[4:5]
	s_xor_b64 s[0:1], exec, s[0:1]
	s_andn2_saveexec_b64 s[4:5], s[0:1]
	s_cbranch_execz .LBB0_429
	s_waitcnt vmcnt(0)
	v_pk_add_f32 v[70:71], v[70:71], v[106:107]
	v_pk_add_f32 v[68:69], v[68:69], v[104:105]
	v_pk_add_f32 v[64:65], v[64:65], v[108:109]
	v_pk_add_f32 v[66:67], v[66:67], v[110:111]
	v_mul_f32_e32 v68, 0xbfb8aa3b, v68
	v_mul_f32_e32 v64, 0xbfb8aa3b, v64
	v_mul_f32_e32 v69, 0xbfb8aa3b, v69
	v_mul_f32_e32 v65, 0xbfb8aa3b, v65
	v_mul_f32_e32 v70, 0xbfb8aa3b, v70
	v_mul_f32_e32 v66, 0xbfb8aa3b, v66
	v_mul_f32_e32 v71, 0xbfb8aa3b, v71
	v_mul_f32_e32 v67, 0xbfb8aa3b, v67
	v_exp_f32_e32 v68, v68
	v_exp_f32_e32 v64, v64
	v_exp_f32_e32 v69, v69
	v_exp_f32_e32 v65, v65
	v_exp_f32_e32 v70, v70
	v_exp_f32_e32 v66, v66
	v_exp_f32_e32 v71, v71
	v_exp_f32_e32 v67, v67
	v_add_f32_e32 v68, 1.0, v68
	v_add_f32_e32 v64, 1.0, v64
	v_add_f32_e32 v69, 1.0, v69
	v_add_f32_e32 v65, 1.0, v65
	v_add_f32_e32 v70, 1.0, v70
	v_add_f32_e32 v66, 1.0, v66
	v_add_f32_e32 v71, 1.0, v71
	v_add_f32_e32 v67, 1.0, v67
	v_rcp_f32_e32 v68, v68
	v_rcp_f32_e32 v64, v64
	v_rcp_f32_e32 v69, v69
	v_rcp_f32_e32 v65, v65
	v_rcp_f32_e32 v70, v70
	v_rcp_f32_e32 v66, v66
	v_rcp_f32_e32 v71, v71
	v_rcp_f32_e32 v67, v67
.LBB0_429:
	s_or_b64 exec, exec, s[4:5]
	v_add_u32_e32 v72, 0xb0, v158
	v_ashrrev_i32_e32 v73, 31, v72
	s_and_saveexec_b64 s[0:1], vcc
	s_xor_b64 s[0:1], exec, s[0:1]
	v_mov_b64_e32 v[76:77], s[6:7]
	s_movk_i32 s4, 0x5a00
	v_mad_i64_i32 v[76:77], s[4:5], v72, s4, v[76:77]
	v_lshl_add_u64 v[84:85], v[184:185], 1, v[76:77]
	s_or_saveexec_b64 s[0:1], s[0:1]
	v_lshlrev_b64 v[76:77], 5, v[72:73]
	s_xor_b64 exec, exec, s[0:1]
	v_lshl_add_u64 v[84:85], v[132:133], 0, v[76:77]
	v_mov_b32_e32 v129, v185
	v_lshl_add_u64 v[84:85], v[84:85], 0, v[128:129]
	s_or_b64 exec, exec, s[0:1]
	v_cvt_pk_bf16_f32 v68, v68, v69
	v_cvt_pk_bf16_f32 v69, v70, v71
	v_cvt_pk_bf16_f32 v70, v64, v65
	v_cvt_pk_bf16_f32 v71, v66, v67
	v_add_u32_e32 v64, 0xffffec90, v184
	s_movk_i32 s0, 0x17ff
	v_lshl_add_u64 v[206:207], v[84:85], 0, v[208:209]
	ds_write_b128 v210, v[68:71]
	ds_read_b128 v[200:203], v211
	s_waitcnt lgkmcnt(2)
	global_store_dwordx4 v[204:205], v[178:181], off
	v_cmp_lt_u32_e64 s[4:5], s0, v64
	s_movk_i32 s0, 0x1800
	v_mov_b32_e32 v68, 0
	v_cmp_gt_u32_e32 vcc, s0, v64
	v_mov_b32_e32 v69, v68
	v_mov_b32_e32 v70, v68
	v_mov_b32_e32 v71, v68
	v_mov_b32_e32 v64, v68
	v_mov_b32_e32 v65, v68
	v_mov_b32_e32 v66, v68
	v_mov_b32_e32 v67, v68
	s_and_saveexec_b64 s[0:1], vcc
	s_cbranch_execz .LBB0_435
	s_movk_i32 s16, 0xb240
	s_mov_b32 s17, -1
	v_add_co_u32_e32 v66, vcc, 0xffffc000, v160
	v_lshl_add_u64 v[64:65], v[160:161], 0, s[16:17]
	s_nop 0
	v_addc_co_u32_e32 v67, vcc, -1, v161, vcc
	global_load_dwordx4 v[68:71], v[66:67], off offset:-3520
	s_nop 0
	global_load_dwordx4 v[64:67], v[64:65], off offset:16

; #define GAS __attribute__((address_space(1)))
; DI unsigned pk2(float lo, float hi) { f32x2 v = {lo, hi}; bf16x2_t r = __builtin_convertvector(v, bf16x2_t); return __builtin_bit_cast(unsigned, r); }
; DI float sigmoidf_(float x) { return __builtin_amdgcn_rcpf(1.f + __expf(-x)); }
;     DI bool operator()(AccT& acc, const Unit& u, int wr, int wc, int fr, int fq) const {
;     ...
;         for (int bj = 0; bj < 2; ++bj) {
;             const int col = col0 + bj * HALF; const bool gate = (col >= ZC_GATE) && (col < ZC_VRES); const bool s5c = col < S5W;
;             f32x4 b0 = {0.f, 0.f, 0.f, 0.f}, b1 = b0;
;             if (gate) { b0 = *(const GAS f32x4*)(gbias + (col - ZC_GATE)); b1 = *(const GAS f32x4*)(gbias + (col - ZC_GATE) + 4); }
; #pragma unroll
;             for (int ai = 0; ai < 2; ++ai)
; #pragma unroll
;                 for (int m = 0; m < 4; ++m) {
;                     f32x4 v0 = acc[ai][bj][m][0] * rsv[ai][m], v1 = acc[ai][bj][m][1] * rsv[ai][m];
;                     if (gate) { v0 += b0; v1 += b1;
; #pragma unroll
;                         for (int e = 0; e < 4; ++e) { v0[e] = sigmoidf_(v0[e]); v1[e] = sigmoidf_(v1[e]); } }
;                     u32x4 w; w.x = pk2(v0[0], v0[1]); w.y = pk2(v0[2], v0[3]); w.z = pk2(v1[0], v1[1]); w.w = pk2(v1[2], v1[3]);
;                     if (s5c) *(GAS u32x4*)(ZS5 + ((size_t)(col >> 4) * M + (row0 + ai * HALF + m * 16)) * 16 + (col & 8)) = w;
;                     else *(GAS u32x4*)(Z + (size_t)(row0 + ai * HALF + m * 16) * ZP + col) = w;
;                 }
.LBB0_437:
	s_or_b64 exec, exec, s[16:17]
	v_or_b32_e32 v56, 0x80, v184
	s_movk_i32 s0, 0x2ff
	v_cmp_lt_i32_e32 vcc, s0, v56
	s_and_saveexec_b64 s[0:1], vcc
	s_xor_b64 s[0:1], exec, s[0:1]
	v_mov_b64_e32 v[86:87], s[6:7]
	s_movk_i32 s16, 0x5a00
	v_mad_i64_i32 v[86:87], s[16:17], v158, s16, v[86:87]
	v_lshl_add_u64 v[86:87], v[184:185], 1, v[86:87]
	s_mov_b64 s[16:17], 0x100
	v_lshl_add_u64 v[86:87], v[86:87], 0, s[16:17]
	s_or_saveexec_b64 s[0:1], s[0:1]
	v_ashrrev_i32_e32 v56, 4, v56
	v_ashrrev_i32_e32 v57, 31, v56
	v_lshlrev_b64 v[56:57], 19, v[56:57]
	v_lshl_add_u64 v[56:57], s[10:11], 0, v[56:57]
	s_xor_b64 exec, exec, s[0:1]
	v_lshl_add_u64 v[86:87], v[56:57], 0, v[130:131]
	v_mov_b32_e32 v129, v185
	v_lshl_add_u64 v[86:87], v[86:87], 0, v[128:129]
	s_or_b64 exec, exec, s[0:1]
	v_mov_b32_e32 v156, v157
	v_cvt_pk_bf16_f32 v60, v60, v61
	v_cvt_pk_bf16_f32 v61, v62, v63
	v_cvt_pk_bf16_f32 v62, v58, v59
	v_mov_b32_e32 v58, v157
	v_mov_b32_e32 v59, v157
	v_cvt_pk_bf16_f32 v63, v84, v85
	v_pk_mul_f32 v[54:55], v[54:55], v[58:59]
	v_pk_mul_f32 v[52:53], v[52:53], v[156:157]
	v_pk_mul_f32 v[50:51], v[50:51], v[58:59]
	v_pk_mul_f32 v[48:49], v[48:49], v[156:157]
	v_lshl_add_u64 v[204:205], v[86:87], 0, v[208:209]
	ds_write_b128 v210, v[60:63]
	ds_read_b128 v[178:181], v211
	s_waitcnt lgkmcnt(2)
	global_store_dwordx4 v[206:207], v[200:203], off
	s_and_saveexec_b64 s[0:1], s[4:5]
	s_xor_b64 s[0:1], exec, s[0:1]
	s_andn2_saveexec_b64 s[16:17], s[0:1]
	s_cbranch_execz .LBB0_443
	s_waitcnt vmcnt(0)
	v_pk_add_f32 v[54:55], v[54:55], v[70:71]
	v_pk_add_f32 v[52:53], v[52:53], v[68:69]
	v_pk_add_f32 v[48:49], v[48:49], v[64:65]
	v_pk_add_f32 v[50:51], v[50:51], v[66:67]
	v_mul_f32_e32 v52, 0xbfb8aa3b, v52
	v_mul_f32_e32 v48, 0xbfb8aa3b, v48
	v_mul_f32_e32 v53, 0xbfb8aa3b, v53
	v_mul_f32_e32 v49, 0xbfb8aa3b, v49
	v_mul_f32_e32 v54, 0xbfb8aa3b, v54
	v_mul_f32_e32 v50, 0xbfb8aa3b, v50
	v_mul_f32_e32 v55, 0xbfb8aa3b, v55
	v_mul_f32_e32 v51, 0xbfb8aa3b, v51
	v_exp_f32_e32 v52, v52
	v_exp_f32_e32 v48, v48
	v_exp_f32_e32 v53, v53
	v_exp_f32_e32 v49, v49
	v_exp_f32_e32 v54, v54
	v_exp_f32_e32 v50, v50
	v_exp_f32_e32 v55, v55
	v_exp_f32_e32 v51, v51
	v_add_f32_e32 v52, 1.0, v52
	v_add_f32_e32 v48, 1.0, v48
	v_add_f32_e32 v53, 1.0, v53
	v_add_f32_e32 v49, 1.0, v49
	v_add_f32_e32 v54, 1.0, v54
	v_add_f32_e32 v50, 1.0, v50
	v_add_f32_e32 v55, 1.0, v55
	v_add_f32_e32 v51, 1.0, v51
	v_rcp_f32_e32 v52, v52
	v_rcp_f32_e32 v48, v48
	v_rcp_f32_e32 v53, v53
	v_rcp_f32_e32 v49, v49
	v_rcp_f32_e32 v54, v54
	v_rcp_f32_e32 v50, v50
	v_rcp_f32_e32 v55, v55
	v_rcp_f32_e32 v51, v51

; #define GAS __attribute__((address_space(1)))
; DI unsigned pk2(float lo, float hi) { f32x2 v = {lo, hi}; bf16x2_t r = __builtin_convertvector(v, bf16x2_t); return __builtin_bit_cast(unsigned, r); }
; DI float sigmoidf_(float x) { return __builtin_amdgcn_rcpf(1.f + __expf(-x)); }
;     DI bool operator()(AccT& acc, const Unit& u, int wr, int wc, int fr, int fq) const {
;     ...
;         for (int bj = 0; bj < 2; ++bj) {
;             const int col = col0 + bj * HALF; const bool gate = (col >= ZC_GATE) && (col < ZC_VRES); const bool s5c = col < S5W;
;             f32x4 b0 = {0.f, 0.f, 0.f, 0.f}, b1 = b0;
;             if (gate) { b0 = *(const GAS f32x4*)(gbias + (col - ZC_GATE)); b1 = *(const GAS f32x4*)(gbias + (col - ZC_GATE) + 4); }
; #pragma unroll
;             for (int ai = 0; ai < 2; ++ai)
; #pragma unroll
;                 for (int m = 0; m < 4; ++m) {
;                     f32x4 v0 = acc[ai][bj][m][0] * rsv[ai][m], v1 = acc[ai][bj][m][1] * rsv[ai][m];
;                     if (gate) { v0 += b0; v1 += b1;
; #pragma unroll
;                         for (int e = 0; e < 4; ++e) { v0[e] = sigmoidf_(v0[e]); v1[e] = sigmoidf_(v1[e]); } }
;                     u32x4 w; w.x = pk2(v0[0], v0[1]); w.y = pk2(v0[2], v0[3]); w.z = pk2(v1[0], v1[1]); w.w = pk2(v1[2], v1[3]);
;                     if (s5c) *(GAS u32x4*)(ZS5 + ((size_t)(col >> 4) * M + (row0 + ai * HALF + m * 16)) * 16 + (col & 8)) = w;
;                     else *(GAS u32x4*)(Z + (size_t)(row0 + ai * HALF + m * 16) * ZP + col) = w;
;                 }
.LBB0_447:
	s_or_b64 exec, exec, s[0:1]
	v_mov_b32_e32 v60, v154
	v_mov_b32_e32 v61, v154
	v_cvt_pk_bf16_f32 v52, v52, v53
	v_cvt_pk_bf16_f32 v53, v54, v55
	v_cvt_pk_bf16_f32 v54, v48, v49
	v_mov_b32_e32 v48, v154
	v_mov_b32_e32 v49, v154
	v_cvt_pk_bf16_f32 v55, v50, v51
	v_pk_mul_f32 v[46:47], v[46:47], v[48:49]
	v_pk_mul_f32 v[44:45], v[44:45], v[60:61]
	v_pk_mul_f32 v[42:43], v[42:43], v[48:49]
	v_pk_mul_f32 v[40:41], v[40:41], v[60:61]
	v_lshl_add_u64 v[206:207], v[58:59], 0, v[208:209]
	ds_write_b128 v210, v[52:55]
	ds_read_b128 v[200:203], v211
	s_waitcnt lgkmcnt(2)
	global_store_dwordx4 v[204:205], v[178:181], off
	s_and_saveexec_b64 s[0:1], s[4:5]
	s_xor_b64 s[0:1], exec, s[0:1]
	s_andn2_saveexec_b64 s[16:17], s[0:1]
	s_cbranch_execz .LBB0_449
	s_waitcnt vmcnt(0)
	v_pk_add_f32 v[46:47], v[46:47], v[70:71]
	v_pk_add_f32 v[44:45], v[44:45], v[68:69]
	v_pk_add_f32 v[40:41], v[40:41], v[64:65]
	v_pk_add_f32 v[42:43], v[42:43], v[66:67]
	v_mul_f32_e32 v44, 0xbfb8aa3b, v44
	v_mul_f32_e32 v40, 0xbfb8aa3b, v40
	v_mul_f32_e32 v45, 0xbfb8aa3b, v45
	v_mul_f32_e32 v41, 0xbfb8aa3b, v41
	v_mul_f32_e32 v46, 0xbfb8aa3b, v46
	v_mul_f32_e32 v42, 0xbfb8aa3b, v42
	v_mul_f32_e32 v47, 0xbfb8aa3b, v47
	v_mul_f32_e32 v43, 0xbfb8aa3b, v43
	v_exp_f32_e32 v44, v44
	v_exp_f32_e32 v40, v40
	v_exp_f32_e32 v45, v45
	v_exp_f32_e32 v41, v41
	v_exp_f32_e32 v46, v46
	v_exp_f32_e32 v42, v42
	v_exp_f32_e32 v47, v47
	v_exp_f32_e32 v43, v43
	v_add_f32_e32 v44, 1.0, v44
	v_add_f32_e32 v40, 1.0, v40
	v_add_f32_e32 v45, 1.0, v45
	v_add_f32_e32 v41, 1.0, v41
	v_add_f32_e32 v46, 1.0, v46
	v_add_f32_e32 v42, 1.0, v42
	v_add_f32_e32 v47, 1.0, v47
	v_add_f32_e32 v43, 1.0, v43
	v_rcp_f32_e32 v44, v44
	v_rcp_f32_e32 v40, v40
	v_rcp_f32_e32 v45, v45
	v_rcp_f32_e32 v41, v41
	v_rcp_f32_e32 v46, v46
	v_rcp_f32_e32 v42, v42
	v_rcp_f32_e32 v47, v47
	v_rcp_f32_e32 v43, v43

; #define GAS __attribute__((address_space(1)))
; DI unsigned pk2(float lo, float hi) { f32x2 v = {lo, hi}; bf16x2_t r = __builtin_convertvector(v, bf16x2_t); return __builtin_bit_cast(unsigned, r); }
; DI float sigmoidf_(float x) { return __builtin_amdgcn_rcpf(1.f + __expf(-x)); }
;     DI bool operator()(AccT& acc, const Unit& u, int wr, int wc, int fr, int fq) const {
;     ...
;         for (int bj = 0; bj < 2; ++bj) {
;             const int col = col0 + bj * HALF; const bool gate = (col >= ZC_GATE) && (col < ZC_VRES); const bool s5c = col < S5W;
;             f32x4 b0 = {0.f, 0.f, 0.f, 0.f}, b1 = b0;
;             if (gate) { b0 = *(const GAS f32x4*)(gbias + (col - ZC_GATE)); b1 = *(const GAS f32x4*)(gbias + (col - ZC_GATE) + 4); }
; #pragma unroll
;             for (int ai = 0; ai < 2; ++ai)
; #pragma unroll
;                 for (int m = 0; m < 4; ++m) {
;                     f32x4 v0 = acc[ai][bj][m][0] * rsv[ai][m], v1 = acc[ai][bj][m][1] * rsv[ai][m];
;                     if (gate) { v0 += b0; v1 += b1;
; #pragma unroll
;                         for (int e = 0; e < 4; ++e) { v0[e] = sigmoidf_(v0[e]); v1[e] = sigmoidf_(v1[e]); } }
;                     u32x4 w; w.x = pk2(v0[0], v0[1]); w.y = pk2(v0[2], v0[3]); w.z = pk2(v1[0], v1[1]); w.w = pk2(v1[2], v1[3]);
;                     if (s5c) *(GAS u32x4*)(ZS5 + ((size_t)(col >> 4) * M + (row0 + ai * HALF + m * 16)) * 16 + (col & 8)) = w;
;                     else *(GAS u32x4*)(Z + (size_t)(row0 + ai * HALF + m * 16) * ZP + col) = w;
;                 }
.LBB0_453:
	s_or_b64 exec, exec, s[0:1]
	v_mov_b32_e32 v154, v155
	v_cvt_pk_bf16_f32 v44, v44, v45
	v_cvt_pk_bf16_f32 v45, v46, v47
	v_cvt_pk_bf16_f32 v46, v40, v41
	v_mov_b32_e32 v40, v155
	v_mov_b32_e32 v41, v155
	v_cvt_pk_bf16_f32 v47, v42, v43
	v_pk_mul_f32 v[38:39], v[38:39], v[40:41]
	v_pk_mul_f32 v[36:37], v[36:37], v[154:155]
	v_pk_mul_f32 v[34:35], v[34:35], v[40:41]
	v_pk_mul_f32 v[32:33], v[32:33], v[154:155]
	v_lshl_add_u64 v[204:205], v[48:49], 0, v[208:209]
	ds_write_b128 v210, v[44:47]
	ds_read_b128 v[178:181], v211
	s_waitcnt lgkmcnt(2)
	global_store_dwordx4 v[206:207], v[200:203], off
	s_and_saveexec_b64 s[0:1], s[4:5]
	s_xor_b64 s[0:1], exec, s[0:1]
	s_andn2_saveexec_b64 s[16:17], s[0:1]
	s_cbranch_execz .LBB0_455
	s_waitcnt vmcnt(0)
	v_pk_add_f32 v[38:39], v[38:39], v[70:71]
	v_pk_add_f32 v[36:37], v[36:37], v[68:69]
	v_pk_add_f32 v[32:33], v[32:33], v[64:65]
	v_pk_add_f32 v[34:35], v[34:35], v[66:67]
	v_mul_f32_e32 v36, 0xbfb8aa3b, v36
	v_mul_f32_e32 v32, 0xbfb8aa3b, v32
	v_mul_f32_e32 v37, 0xbfb8aa3b, v37
	v_mul_f32_e32 v33, 0xbfb8aa3b, v33
	v_mul_f32_e32 v38, 0xbfb8aa3b, v38
	v_mul_f32_e32 v34, 0xbfb8aa3b, v34
	v_mul_f32_e32 v39, 0xbfb8aa3b, v39
	v_mul_f32_e32 v35, 0xbfb8aa3b, v35
	v_exp_f32_e32 v36, v36
	v_exp_f32_e32 v32, v32
	v_exp_f32_e32 v37, v37
	v_exp_f32_e32 v33, v33
	v_exp_f32_e32 v38, v38
	v_exp_f32_e32 v34, v34
	v_exp_f32_e32 v39, v39
	v_exp_f32_e32 v35, v35
	v_add_f32_e32 v36, 1.0, v36
	v_add_f32_e32 v32, 1.0, v32
	v_add_f32_e32 v37, 1.0, v37
	v_add_f32_e32 v33, 1.0, v33
	v_add_f32_e32 v38, 1.0, v38
	v_add_f32_e32 v34, 1.0, v34
	v_add_f32_e32 v39, 1.0, v39
	v_add_f32_e32 v35, 1.0, v35
	v_rcp_f32_e32 v36, v36
	v_rcp_f32_e32 v32, v32
	v_rcp_f32_e32 v37, v37
	v_rcp_f32_e32 v33, v33
	v_rcp_f32_e32 v38, v38
	v_rcp_f32_e32 v34, v34
	v_rcp_f32_e32 v39, v39
	v_rcp_f32_e32 v35, v35

; #define GAS __attribute__((address_space(1)))
; DI unsigned pk2(float lo, float hi) { f32x2 v = {lo, hi}; bf16x2_t r = __builtin_convertvector(v, bf16x2_t); return __builtin_bit_cast(unsigned, r); }
; DI float sigmoidf_(float x) { return __builtin_amdgcn_rcpf(1.f + __expf(-x)); }
;     DI bool operator()(AccT& acc, const Unit& u, int wr, int wc, int fr, int fq) const {
;     ...
;         for (int bj = 0; bj < 2; ++bj) {
;             const int col = col0 + bj * HALF; const bool gate = (col >= ZC_GATE) && (col < ZC_VRES); const bool s5c = col < S5W;
;             f32x4 b0 = {0.f, 0.f, 0.f, 0.f}, b1 = b0;
;             if (gate) { b0 = *(const GAS f32x4*)(gbias + (col - ZC_GATE)); b1 = *(const GAS f32x4*)(gbias + (col - ZC_GATE) + 4); }
; #pragma unroll
;             for (int ai = 0; ai < 2; ++ai)
; #pragma unroll
;                 for (int m = 0; m < 4; ++m) {
;                     f32x4 v0 = acc[ai][bj][m][0] * rsv[ai][m], v1 = acc[ai][bj][m][1] * rsv[ai][m];
;                     if (gate) { v0 += b0; v1 += b1;
; #pragma unroll
;                         for (int e = 0; e < 4; ++e) { v0[e] = sigmoidf_(v0[e]); v1[e] = sigmoidf_(v1[e]); } }
;                     u32x4 w; w.x = pk2(v0[0], v0[1]); w.y = pk2(v0[2], v0[3]); w.z = pk2(v1[0], v1[1]); w.w = pk2(v1[2], v1[3]);
;                     if (s5c) *(GAS u32x4*)(ZS5 + ((size_t)(col >> 4) * M + (row0 + ai * HALF + m * 16)) * 16 + (col & 8)) = w;
;                     else *(GAS u32x4*)(Z + (size_t)(row0 + ai * HALF + m * 16) * ZP + col) = w;
;                 }
.LBB0_459:
	s_or_b64 exec, exec, s[0:1]
	v_mov_b32_e32 v42, v152
	v_mov_b32_e32 v43, v152
	v_cvt_pk_bf16_f32 v36, v36, v37
	v_cvt_pk_bf16_f32 v37, v38, v39
	v_cvt_pk_bf16_f32 v38, v32, v33
	v_mov_b32_e32 v32, v152
	v_mov_b32_e32 v33, v152
	v_cvt_pk_bf16_f32 v39, v34, v35
	v_pk_mul_f32 v[30:31], v[30:31], v[32:33]
	v_pk_mul_f32 v[28:29], v[28:29], v[42:43]
	v_pk_mul_f32 v[26:27], v[26:27], v[32:33]
	v_pk_mul_f32 v[24:25], v[24:25], v[42:43]
	v_lshl_add_u64 v[206:207], v[40:41], 0, v[208:209]
	ds_write_b128 v210, v[36:39]
	ds_read_b128 v[200:203], v211
	s_waitcnt lgkmcnt(2)
	global_store_dwordx4 v[204:205], v[178:181], off
	s_and_saveexec_b64 s[0:1], s[4:5]
	s_xor_b64 s[0:1], exec, s[0:1]
	s_andn2_saveexec_b64 s[16:17], s[0:1]
	s_cbranch_execz .LBB0_461
	s_waitcnt vmcnt(0)
	v_pk_add_f32 v[30:31], v[30:31], v[70:71]
	v_pk_add_f32 v[28:29], v[28:29], v[68:69]
	v_pk_add_f32 v[24:25], v[24:25], v[64:65]
	v_pk_add_f32 v[26:27], v[26:27], v[66:67]
	v_mul_f32_e32 v28, 0xbfb8aa3b, v28
	v_mul_f32_e32 v24, 0xbfb8aa3b, v24
	v_mul_f32_e32 v29, 0xbfb8aa3b, v29
	v_mul_f32_e32 v25, 0xbfb8aa3b, v25
	v_mul_f32_e32 v30, 0xbfb8aa3b, v30
	v_mul_f32_e32 v26, 0xbfb8aa3b, v26
	v_mul_f32_e32 v31, 0xbfb8aa3b, v31
	v_mul_f32_e32 v27, 0xbfb8aa3b, v27
	v_exp_f32_e32 v28, v28
	v_exp_f32_e32 v24, v24
	v_exp_f32_e32 v29, v29
	v_exp_f32_e32 v25, v25
	v_exp_f32_e32 v30, v30
	v_exp_f32_e32 v26, v26
	v_exp_f32_e32 v31, v31
	v_exp_f32_e32 v27, v27
	v_add_f32_e32 v28, 1.0, v28
	v_add_f32_e32 v24, 1.0, v24
	v_add_f32_e32 v29, 1.0, v29
	v_add_f32_e32 v25, 1.0, v25
	v_add_f32_e32 v30, 1.0, v30
	v_add_f32_e32 v26, 1.0, v26
	v_add_f32_e32 v31, 1.0, v31
	v_add_f32_e32 v27, 1.0, v27
	v_rcp_f32_e32 v28, v28
	v_rcp_f32_e32 v24, v24
	v_rcp_f32_e32 v29, v29
	v_rcp_f32_e32 v25, v25
	v_rcp_f32_e32 v30, v30
	v_rcp_f32_e32 v26, v26
	v_rcp_f32_e32 v31, v31
	v_rcp_f32_e32 v27, v27

; #define GAS __attribute__((address_space(1)))
; DI unsigned pk2(float lo, float hi) { f32x2 v = {lo, hi}; bf16x2_t r = __builtin_convertvector(v, bf16x2_t); return __builtin_bit_cast(unsigned, r); }
; DI float sigmoidf_(float x) { return __builtin_amdgcn_rcpf(1.f + __expf(-x)); }
;     DI bool operator()(AccT& acc, const Unit& u, int wr, int wc, int fr, int fq) const {
;     ...
;         for (int bj = 0; bj < 2; ++bj) {
;             const int col = col0 + bj * HALF; const bool gate = (col >= ZC_GATE) && (col < ZC_VRES); const bool s5c = col < S5W;
;             f32x4 b0 = {0.f, 0.f, 0.f, 0.f}, b1 = b0;
;             if (gate) { b0 = *(const GAS f32x4*)(gbias + (col - ZC_GATE)); b1 = *(const GAS f32x4*)(gbias + (col - ZC_GATE) + 4); }
; #pragma unroll
;             for (int ai = 0; ai < 2; ++ai)
; #pragma unroll
;                 for (int m = 0; m < 4; ++m) {
;                     f32x4 v0 = acc[ai][bj][m][0] * rsv[ai][m], v1 = acc[ai][bj][m][1] * rsv[ai][m];
;                     if (gate) { v0 += b0; v1 += b1;
; #pragma unroll
;                         for (int e = 0; e < 4; ++e) { v0[e] = sigmoidf_(v0[e]); v1[e] = sigmoidf_(v1[e]); } }
;                     u32x4 w; w.x = pk2(v0[0], v0[1]); w.y = pk2(v0[2], v0[3]); w.z = pk2(v1[0], v1[1]); w.w = pk2(v1[2], v1[3]);
;                     if (s5c) *(GAS u32x4*)(ZS5 + ((size_t)(col >> 4) * M + (row0 + ai * HALF + m * 16)) * 16 + (col & 8)) = w;
;                     else *(GAS u32x4*)(Z + (size_t)(row0 + ai * HALF + m * 16) * ZP + col) = w;
;                 }
.LBB0_465:
	s_or_b64 exec, exec, s[0:1]
	v_mov_b32_e32 v152, v153
	v_cvt_pk_bf16_f32 v28, v28, v29
	v_cvt_pk_bf16_f32 v29, v30, v31
	v_cvt_pk_bf16_f32 v30, v24, v25
	v_mov_b32_e32 v24, v153
	v_mov_b32_e32 v25, v153
	v_cvt_pk_bf16_f32 v31, v26, v27
	v_pk_mul_f32 v[22:23], v[22:23], v[24:25]
	v_pk_mul_f32 v[20:21], v[20:21], v[152:153]
	v_pk_mul_f32 v[18:19], v[18:19], v[24:25]
	v_pk_mul_f32 v[16:17], v[16:17], v[152:153]
	v_lshl_add_u64 v[204:205], v[32:33], 0, v[208:209]
	ds_write_b128 v210, v[28:31]
	ds_read_b128 v[178:181], v211
	s_waitcnt lgkmcnt(2)
	global_store_dwordx4 v[206:207], v[200:203], off
	s_and_saveexec_b64 s[0:1], s[4:5]
	s_xor_b64 s[0:1], exec, s[0:1]
	s_andn2_saveexec_b64 s[16:17], s[0:1]
	s_cbranch_execz .LBB0_467
	s_waitcnt vmcnt(0)
	v_pk_add_f32 v[22:23], v[22:23], v[70:71]
	v_pk_add_f32 v[20:21], v[20:21], v[68:69]
	v_pk_add_f32 v[16:17], v[16:17], v[64:65]
	v_pk_add_f32 v[18:19], v[18:19], v[66:67]
	v_mul_f32_e32 v20, 0xbfb8aa3b, v20
	v_mul_f32_e32 v16, 0xbfb8aa3b, v16
	v_mul_f32_e32 v21, 0xbfb8aa3b, v21
	v_mul_f32_e32 v17, 0xbfb8aa3b, v17
	v_mul_f32_e32 v22, 0xbfb8aa3b, v22
	v_mul_f32_e32 v18, 0xbfb8aa3b, v18
	v_mul_f32_e32 v23, 0xbfb8aa3b, v23
	v_mul_f32_e32 v19, 0xbfb8aa3b, v19
	v_exp_f32_e32 v20, v20
	v_exp_f32_e32 v16, v16
	v_exp_f32_e32 v21, v21
	v_exp_f32_e32 v17, v17
	v_exp_f32_e32 v22, v22
	v_exp_f32_e32 v18, v18
	v_exp_f32_e32 v23, v23
	v_exp_f32_e32 v19, v19
	v_add_f32_e32 v20, 1.0, v20
	v_add_f32_e32 v16, 1.0, v16
	v_add_f32_e32 v21, 1.0, v21
	v_add_f32_e32 v17, 1.0, v17
	v_add_f32_e32 v22, 1.0, v22
	v_add_f32_e32 v18, 1.0, v18
	v_add_f32_e32 v23, 1.0, v23
	v_add_f32_e32 v19, 1.0, v19
	v_rcp_f32_e32 v20, v20
	v_rcp_f32_e32 v16, v16
	v_rcp_f32_e32 v21, v21
	v_rcp_f32_e32 v17, v17
	v_rcp_f32_e32 v22, v22
	v_rcp_f32_e32 v18, v18
	v_rcp_f32_e32 v23, v23
	v_rcp_f32_e32 v19, v19

; #define GAS __attribute__((address_space(1)))
; DI unsigned pk2(float lo, float hi) { f32x2 v = {lo, hi}; bf16x2_t r = __builtin_convertvector(v, bf16x2_t); return __builtin_bit_cast(unsigned, r); }
; DI float sigmoidf_(float x) { return __builtin_amdgcn_rcpf(1.f + __expf(-x)); }
;     DI bool operator()(AccT& acc, const Unit& u, int wr, int wc, int fr, int fq) const {
;     ...
;         for (int bj = 0; bj < 2; ++bj) {
;             const int col = col0 + bj * HALF; const bool gate = (col >= ZC_GATE) && (col < ZC_VRES); const bool s5c = col < S5W;
;             f32x4 b0 = {0.f, 0.f, 0.f, 0.f}, b1 = b0;
;             if (gate) { b0 = *(const GAS f32x4*)(gbias + (col - ZC_GATE)); b1 = *(const GAS f32x4*)(gbias + (col - ZC_GATE) + 4); }
; #pragma unroll
;             for (int ai = 0; ai < 2; ++ai)
; #pragma unroll
;                 for (int m = 0; m < 4; ++m) {
;                     f32x4 v0 = acc[ai][bj][m][0] * rsv[ai][m], v1 = acc[ai][bj][m][1] * rsv[ai][m];
;                     if (gate) { v0 += b0; v1 += b1;
; #pragma unroll
;                         for (int e = 0; e < 4; ++e) { v0[e] = sigmoidf_(v0[e]); v1[e] = sigmoidf_(v1[e]); } }
;                     u32x4 w; w.x = pk2(v0[0], v0[1]); w.y = pk2(v0[2], v0[3]); w.z = pk2(v1[0], v1[1]); w.w = pk2(v1[2], v1[3]);
;                     if (s5c) *(GAS u32x4*)(ZS5 + ((size_t)(col >> 4) * M + (row0 + ai * HALF + m * 16)) * 16 + (col & 8)) = w;
;                     else *(GAS u32x4*)(Z + (size_t)(row0 + ai * HALF + m * 16) * ZP + col) = w;
;                 }
.LBB0_471:
	s_or_b64 exec, exec, s[0:1]
	v_mov_b32_e32 v26, v150
	v_mov_b32_e32 v27, v150
	v_cvt_pk_bf16_f32 v20, v20, v21
	v_cvt_pk_bf16_f32 v21, v22, v23
	v_cvt_pk_bf16_f32 v22, v16, v17
	v_mov_b32_e32 v16, v150
	v_mov_b32_e32 v17, v150
	v_cvt_pk_bf16_f32 v23, v18, v19
	v_pk_mul_f32 v[14:15], v[14:15], v[16:17]
	v_pk_mul_f32 v[12:13], v[12:13], v[26:27]
	v_pk_mul_f32 v[10:11], v[10:11], v[16:17]
	v_pk_mul_f32 v[8:9], v[8:9], v[26:27]
	v_lshl_add_u64 v[206:207], v[24:25], 0, v[208:209]
	ds_write_b128 v210, v[20:23]
	ds_read_b128 v[200:203], v211
	s_waitcnt lgkmcnt(2)
	global_store_dwordx4 v[204:205], v[178:181], off
	s_and_saveexec_b64 s[0:1], s[4:5]
	s_xor_b64 s[0:1], exec, s[0:1]
	s_andn2_saveexec_b64 s[16:17], s[0:1]
	s_cbranch_execz .LBB0_473
	s_waitcnt vmcnt(0)
	v_pk_add_f32 v[14:15], v[14:15], v[70:71]
	v_pk_add_f32 v[12:13], v[12:13], v[68:69]
	v_pk_add_f32 v[8:9], v[8:9], v[64:65]
	v_pk_add_f32 v[10:11], v[10:11], v[66:67]
	v_mul_f32_e32 v12, 0xbfb8aa3b, v12
	v_mul_f32_e32 v8, 0xbfb8aa3b, v8
	v_mul_f32_e32 v13, 0xbfb8aa3b, v13
	v_mul_f32_e32 v9, 0xbfb8aa3b, v9
	v_mul_f32_e32 v14, 0xbfb8aa3b, v14
	v_mul_f32_e32 v10, 0xbfb8aa3b, v10
	v_mul_f32_e32 v15, 0xbfb8aa3b, v15
	v_mul_f32_e32 v11, 0xbfb8aa3b, v11
	v_exp_f32_e32 v12, v12
	v_exp_f32_e32 v8, v8
	v_exp_f32_e32 v13, v13
	v_exp_f32_e32 v9, v9
	v_exp_f32_e32 v14, v14
	v_exp_f32_e32 v10, v10
	v_exp_f32_e32 v15, v15
	v_exp_f32_e32 v11, v11
	v_add_f32_e32 v12, 1.0, v12
	v_add_f32_e32 v8, 1.0, v8
	v_add_f32_e32 v13, 1.0, v13
	v_add_f32_e32 v9, 1.0, v9
	v_add_f32_e32 v14, 1.0, v14
	v_add_f32_e32 v10, 1.0, v10
	v_add_f32_e32 v15, 1.0, v15
	v_add_f32_e32 v11, 1.0, v11
	v_rcp_f32_e32 v12, v12
	v_rcp_f32_e32 v8, v8
	v_rcp_f32_e32 v13, v13
	v_rcp_f32_e32 v9, v9
	v_rcp_f32_e32 v14, v14
	v_rcp_f32_e32 v10, v10
	v_rcp_f32_e32 v15, v15
	v_rcp_f32_e32 v11, v11

; #define GAS __attribute__((address_space(1)))
; DI unsigned pk2(float lo, float hi) { f32x2 v = {lo, hi}; bf16x2_t r = __builtin_convertvector(v, bf16x2_t); return __builtin_bit_cast(unsigned, r); }
; DI float sigmoidf_(float x) { return __builtin_amdgcn_rcpf(1.f + __expf(-x)); }
;     DI bool operator()(AccT& acc, const Unit& u, int wr, int wc, int fr, int fq) const {
;     ...
;         for (int bj = 0; bj < 2; ++bj) {
;             const int col = col0 + bj * HALF; const bool gate = (col >= ZC_GATE) && (col < ZC_VRES); const bool s5c = col < S5W;
;             f32x4 b0 = {0.f, 0.f, 0.f, 0.f}, b1 = b0;
;             if (gate) { b0 = *(const GAS f32x4*)(gbias + (col - ZC_GATE)); b1 = *(const GAS f32x4*)(gbias + (col - ZC_GATE) + 4); }
; #pragma unroll
;             for (int ai = 0; ai < 2; ++ai)
; #pragma unroll
;                 for (int m = 0; m < 4; ++m) {
;                     f32x4 v0 = acc[ai][bj][m][0] * rsv[ai][m], v1 = acc[ai][bj][m][1] * rsv[ai][m];
;                     if (gate) { v0 += b0; v1 += b1;
; #pragma unroll
;                         for (int e = 0; e < 4; ++e) { v0[e] = sigmoidf_(v0[e]); v1[e] = sigmoidf_(v1[e]); } }
;                     u32x4 w; w.x = pk2(v0[0], v0[1]); w.y = pk2(v0[2], v0[3]); w.z = pk2(v1[0], v1[1]); w.w = pk2(v1[2], v1[3]);
;                     if (s5c) *(GAS u32x4*)(ZS5 + ((size_t)(col >> 4) * M + (row0 + ai * HALF + m * 16)) * 16 + (col & 8)) = w;
;                     else *(GAS u32x4*)(Z + (size_t)(row0 + ai * HALF + m * 16) * ZP + col) = w;
;                 }
.LBB0_477:
	s_or_b64 exec, exec, s[0:1]
	v_mov_b32_e32 v150, v151
	v_cvt_pk_bf16_f32 v12, v12, v13
	v_cvt_pk_bf16_f32 v13, v14, v15
	v_cvt_pk_bf16_f32 v14, v8, v9
	v_mov_b32_e32 v8, v151
	v_mov_b32_e32 v9, v151
	v_cvt_pk_bf16_f32 v15, v10, v11
	v_pk_mul_f32 v[6:7], v[6:7], v[8:9]
	v_pk_mul_f32 v[4:5], v[4:5], v[150:151]
	v_pk_mul_f32 v[2:3], v[2:3], v[8:9]
	v_pk_mul_f32 v[0:1], v[0:1], v[150:151]
	v_lshl_add_u64 v[204:205], v[16:17], 0, v[208:209]
	ds_write_b128 v210, v[12:15]
	ds_read_b128 v[178:181], v211
	s_waitcnt lgkmcnt(2)
	global_store_dwordx4 v[206:207], v[200:203], off
	s_and_saveexec_b64 s[0:1], s[4:5]
	s_xor_b64 s[0:1], exec, s[0:1]
	s_cbranch_execz .LBB0_479
	s_andn2_saveexec_b64 s[4:5], s[0:1]
	s_cbranch_execz .LBB0_481
	s_branch .LBB0_480

; #define GAS __attribute__((address_space(1)))
; DI unsigned pk2(float lo, float hi) { f32x2 v = {lo, hi}; bf16x2_t r = __builtin_convertvector(v, bf16x2_t); return __builtin_bit_cast(unsigned, r); }
; DI float sigmoidf_(float x) { return __builtin_amdgcn_rcpf(1.f + __expf(-x)); }
;     DI bool operator()(AccT& acc, const Unit& u, int wr, int wc, int fr, int fq) const {
;     ...
;         for (int bj = 0; bj < 2; ++bj) {
;             const int col = col0 + bj * HALF; const bool gate = (col >= ZC_GATE) && (col < ZC_VRES); const bool s5c = col < S5W;
;             f32x4 b0 = {0.f, 0.f, 0.f, 0.f}, b1 = b0;
;             if (gate) { b0 = *(const GAS f32x4*)(gbias + (col - ZC_GATE)); b1 = *(const GAS f32x4*)(gbias + (col - ZC_GATE) + 4); }
; #pragma unroll
;             for (int ai = 0; ai < 2; ++ai)
; #pragma unroll
;                 for (int m = 0; m < 4; ++m) {
;                     f32x4 v0 = acc[ai][bj][m][0] * rsv[ai][m], v1 = acc[ai][bj][m][1] * rsv[ai][m];
;                     if (gate) { v0 += b0; v1 += b1;
; #pragma unroll
;                         for (int e = 0; e < 4; ++e) { v0[e] = sigmoidf_(v0[e]); v1[e] = sigmoidf_(v1[e]); } }
;                     u32x4 w; w.x = pk2(v0[0], v0[1]); w.y = pk2(v0[2], v0[3]); w.z = pk2(v1[0], v1[1]); w.w = pk2(v1[2], v1[3]);
;                     if (s5c) *(GAS u32x4*)(ZS5 + ((size_t)(col >> 4) * M + (row0 + ai * HALF + m * 16)) * 16 + (col & 8)) = w;
;                     else *(GAS u32x4*)(Z + (size_t)(row0 + ai * HALF + m * 16) * ZP + col) = w;
;                 }
.LBB0_485:
	s_or_b64 exec, exec, s[0:1]
	v_cvt_pk_bf16_f32 v4, v4, v5
	v_cvt_pk_bf16_f32 v5, v6, v7
	v_cvt_pk_bf16_f32 v6, v0, v1
	v_cvt_pk_bf16_f32 v7, v2, v3
	s_andn2_b64 vcc, exec, s[40:41]
	s_mov_b64 s[0:1], -1
	v_lshl_add_u64 v[206:207], v[8:9], 0, v[208:209]
	ds_write_b128 v210, v[4:7]
	ds_read_b128 v[200:203], v211
	s_waitcnt lgkmcnt(2)
	global_store_dwordx4 v[204:205], v[178:181], off
	s_waitcnt lgkmcnt(0)
	global_store_dwordx4 v[206:207], v[200:203], off
	s_cbranch_vccnz .LBB0_374
	s_andn2_b64 vcc, exec, s[2:3]
	s_cbranch_vccnz .LBB0_373
	s_barrier
	s_branch .LBB0_373

; #define GAS __attribute__((address_space(1)))
; DI unsigned pk2(float lo, float hi) { f32x2 v = {lo, hi}; bf16x2_t r = __builtin_convertvector(v, bf16x2_t); return __builtin_bit_cast(unsigned, r); }
;     DI bool operator()(AccT& acc, const Unit& u, int wr, int wc, int fr, int fq) const {
;         const int row0 = u.pm * BM + wr * 64 + fr, col0 = u.pn * BM + wc * 32 + 8 * fq;
; #pragma unroll
;         for (int ai = 0; ai < 2; ++ai)
; #pragma unroll
;             for (int m = 0; m < 4; ++m) { bf16* rowp = out + (size_t)(row0 + ai * HALF + m * 16) * DFF + col0; const float rsv = rs[row0 + ai * HALF + m * 16];
; #pragma unroll
;                 for (int bj = 0; bj < 2; ++bj) { f32x4 v0 = acc[ai][bj][m][0] * rsv, v1 = acc[ai][bj][m][1] * rsv;
; #pragma unroll
;                     for (int e = 0; e < 4; ++e) { const float a = fmaxf(v0[e], 0.f), b = fmaxf(v1[e], 0.f); v0[e] = a * a; v1[e] = b * b; }
;                     u32x4 w; w.x = pk2(v0[0], v0[1]); w.y = pk2(v0[2], v0[3]); w.z = pk2(v1[0], v1[1]); w.w = pk2(v1[2], v1[3]);
;                     *(GAS u32x4*)(rowp + bj * HALF) = w; } }
.LBB0_1400:
	v_mbcnt_lo_u32_b32 v172, -1, 0
	v_mbcnt_hi_u32_b32 v172, -1, v172
	s_lshl_b32 s98, s90, 10
	s_add_i32 s98, s98, 0x22000
	v_lshl_add_u32 v171, v172, 4, s98
	v_and_b32_e32 v173, 15, v172
	v_lshrrev_b32_e32 v174, 4, v172
	v_lshrrev_b32_e32 v175, 2, v173
	v_lshl_add_u32 v174, v175, 4, v174
	v_and_b32_e32 v175, 3, v173
	v_lshl_add_u32 v174, v175, 2, v174
	v_lshl_add_u32 v170, v174, 4, s98
	v_lshrrev_b32_e32 v174, 4, v172
	v_bfe_u32 v175, v172, 2, 2
	v_lshl_add_u32 v175, v174, 2, v175
	v_sub_u32_e32 v175, v175, v173
	v_and_b32_e32 v173, 3, v172
	v_sub_u32_e32 v173, v173, v174
	v_lshlrev_b32_e32 v173, 4, v173
	s_movk_i32 s98, 0x4000
	v_mad_i32_i24 v168, v175, s98, v173
	v_ashrrev_i32_e32 v169, 31, v168
	v_lshl_add_u32 v140, s24, 8, v144
	v_lshl_add_u32 v148, v140, 2, s42
	ds_read2_b32 v[150:151], v148 offset1:16
	v_lshl_or_b32 v138, s47, 8, v146
	v_ashrrev_i32_e32 v141, 31, v140
	v_ashrrev_i32_e32 v139, 31, v138
	v_lshlrev_b64 v[142:143], 14, v[140:141]
	s_waitcnt lgkmcnt(0)
	v_pk_mul_f32 v[120:121], v[120:121], v[150:151] op_sel_hi:[1,0]
	v_lshl_add_u64 v[152:153], s[6:7], 0, v[142:143]
	v_lshlrev_b64 v[142:143], 1, v[138:139]
	v_pk_mul_f32 v[126:127], v[126:127], v[150:151] op_sel_hi:[1,0]
	v_pk_mul_f32 v[124:125], v[124:125], v[150:151] op_sel_hi:[1,0]
	v_pk_mul_f32 v[122:123], v[122:123], v[150:151] op_sel_hi:[1,0]
	v_max_f32_e32 v120, 0, v120
	v_max_f32_e32 v121, 0, v121
	v_lshl_add_u64 v[138:139], v[152:153], 0, v[142:143]
	v_max_f32_e32 v124, 0, v124
	v_max_f32_e32 v125, 0, v125
	v_pk_mul_f32 v[152:153], v[120:121], v[120:121]
	v_max_f32_e32 v120, 0, v126
	v_max_f32_e32 v122, 0, v122
	v_max_f32_e32 v121, 0, v127
	v_max_f32_e32 v123, 0, v123
	v_pk_mul_f32 v[124:125], v[124:125], v[124:125]
	v_pk_mul_f32 v[126:127], v[120:121], v[120:121]
	v_pk_mul_f32 v[154:155], v[122:123], v[122:123]
	v_pk_mul_f32 v[112:113], v[112:113], v[150:151] op_sel_hi:[1,0]
	v_cvt_pk_bf16_f32 v120, v124, v125
	v_cvt_pk_bf16_f32 v121, v126, v127
	v_cvt_pk_bf16_f32 v122, v152, v153
	v_cvt_pk_bf16_f32 v123, v154, v155
	v_pk_mul_f32 v[118:119], v[118:119], v[150:151] op_sel_hi:[1,0]
	v_pk_mul_f32 v[116:117], v[116:117], v[150:151] op_sel_hi:[1,0]
	v_pk_mul_f32 v[114:115], v[114:115], v[150:151] op_sel_hi:[1,0]
	v_max_f32_e32 v112, 0, v112
	v_max_f32_e32 v113, 0, v113
	v_lshl_add_u64 v[164:165], v[138:139], 0, v[168:169]
	ds_write_b128 v170, v[120:123]
	ds_read_b128 v[156:159], v171
	v_max_f32_e32 v116, 0, v116
	v_max_f32_e32 v117, 0, v117
	v_pk_mul_f32 v[120:121], v[112:113], v[112:113]
	v_max_f32_e32 v112, 0, v118
	v_max_f32_e32 v114, 0, v114
	v_max_f32_e32 v113, 0, v119
	v_max_f32_e32 v115, 0, v115
	v_pk_mul_f32 v[116:117], v[116:117], v[116:117]
	v_pk_mul_f32 v[118:119], v[112:113], v[112:113]
	v_pk_mul_f32 v[122:123], v[114:115], v[114:115]
	v_cvt_pk_bf16_f32 v112, v116, v117
	v_cvt_pk_bf16_f32 v113, v118, v119
	v_cvt_pk_bf16_f32 v114, v120, v121
	v_cvt_pk_bf16_f32 v115, v122, v123
	v_lshl_add_u64 v[166:167], v[138:139], 0, v[168:169]
	ds_write_b128 v170, v[112:115]
	ds_read_b128 v[160:163], v171
	s_waitcnt lgkmcnt(2)
	global_store_dwordx4 v[164:165], v[156:159], off
	s_mov_b64 s[0:1], 0x200000
	s_nop 0
	v_mov_b32_e32 v114, v151
	v_or_b32_e32 v112, 16, v140
	v_pk_mul_f32 v[104:105], v[104:105], v[114:115] op_sel_hi:[1,0]
	v_ashrrev_i32_e32 v113, 31, v112
	v_pk_mul_f32 v[110:111], v[110:111], v[114:115] op_sel_hi:[1,0]
	v_pk_mul_f32 v[108:109], v[108:109], v[114:115] op_sel_hi:[1,0]
	v_pk_mul_f32 v[106:107], v[106:107], v[114:115] op_sel_hi:[1,0]
	v_max_f32_e32 v104, 0, v104
	v_max_f32_e32 v105, 0, v105
	v_lshlrev_b64 v[112:113], 14, v[112:113]
	v_max_f32_e32 v108, 0, v108
	v_max_f32_e32 v109, 0, v109
	v_pk_mul_f32 v[116:117], v[104:105], v[104:105]
	v_max_f32_e32 v104, 0, v110
	v_max_f32_e32 v106, 0, v106
	v_max_f32_e32 v105, 0, v111
	v_max_f32_e32 v107, 0, v107
	v_lshl_add_u64 v[112:113], s[6:7], 0, v[112:113]
	v_pk_mul_f32 v[108:109], v[108:109], v[108:109]
	v_pk_mul_f32 v[110:111], v[104:105], v[104:105]
	v_pk_mul_f32 v[118:119], v[106:107], v[106:107]
	v_pk_mul_f32 v[96:97], v[96:97], v[114:115] op_sel_hi:[1,0]
	v_lshl_add_u64 v[112:113], v[112:113], 0, v[142:143]
	v_cvt_pk_bf16_f32 v104, v108, v109
	v_cvt_pk_bf16_f32 v105, v110, v111
	v_cvt_pk_bf16_f32 v106, v116, v117
	v_cvt_pk_bf16_f32 v107, v118, v119
	v_pk_mul_f32 v[102:103], v[102:103], v[114:115] op_sel_hi:[1,0]
	v_pk_mul_f32 v[100:101], v[100:101], v[114:115] op_sel_hi:[1,0]
	v_pk_mul_f32 v[98:99], v[98:99], v[114:115] op_sel_hi:[1,0]
	v_max_f32_e32 v96, 0, v96
	v_max_f32_e32 v97, 0, v97
	v_lshl_add_u64 v[164:165], v[112:113], 0, v[168:169]
	ds_write_b128 v170, v[104:107]
	ds_read_b128 v[156:159], v171
	s_waitcnt lgkmcnt(2)
	global_store_dwordx4 v[166:167], v[160:163], off offset:256
	v_max_f32_e32 v100, 0, v100
	v_max_f32_e32 v101, 0, v101
	v_pk_mul_f32 v[104:105], v[96:97], v[96:97]
	v_max_f32_e32 v96, 0, v102
	v_max_f32_e32 v98, 0, v98
	v_max_f32_e32 v97, 0, v103
	v_max_f32_e32 v99, 0, v99
	v_pk_mul_f32 v[100:101], v[100:101], v[100:101]
	v_pk_mul_f32 v[102:103], v[96:97], v[96:97]
	v_pk_mul_f32 v[106:107], v[98:99], v[98:99]
	v_cvt_pk_bf16_f32 v96, v100, v101
	v_cvt_pk_bf16_f32 v97, v102, v103
	v_cvt_pk_bf16_f32 v98, v104, v105
	v_cvt_pk_bf16_f32 v99, v106, v107
	v_lshl_add_u64 v[166:167], v[112:113], 0, v[168:169]
	ds_write_b128 v170, v[96:99]
	ds_read_b128 v[160:163], v171
	s_waitcnt lgkmcnt(2)
	global_store_dwordx4 v[164:165], v[156:159], off
	ds_read2_b32 v[98:99], v148 offset0:32 offset1:48
	s_waitcnt lgkmcnt(0)
; #define GAS __attribute__((address_space(1)))
; DI unsigned pk2(float lo, float hi) { f32x2 v = {lo, hi}; bf16x2_t r = __builtin_convertvector(v, bf16x2_t); return __builtin_bit_cast(unsigned, r); }
;     DI bool operator()(AccT& acc, const Unit& u, int wr, int wc, int fr, int fq) const {
;     ...
;             for (int m = 0; m < 4; ++m) { bf16* rowp = out + (size_t)(row0 + ai * HALF + m * 16) * DFF + col0; const float rsv = rs[row0 + ai * HALF + m * 16];
; #pragma unroll
;                 for (int bj = 0; bj < 2; ++bj) { f32x4 v0 = acc[ai][bj][m][0] * rsv, v1 = acc[ai][bj][m][1] * rsv;
; #pragma unroll
;                     for (int e = 0; e < 4; ++e) { const float a = fmaxf(v0[e], 0.f), b = fmaxf(v1[e], 0.f); v0[e] = a * a; v1[e] = b * b; }
;                     u32x4 w; w.x = pk2(v0[0], v0[1]); w.y = pk2(v0[2], v0[3]); w.z = pk2(v1[0], v1[1]); w.w = pk2(v1[2], v1[3]);
;                     *(GAS u32x4*)(rowp + bj * HALF) = w; } }
	v_pk_mul_f32 v[88:89], v[88:89], v[98:99] op_sel_hi:[1,0]
	v_or_b32_e32 v96, 32, v140
	v_ashrrev_i32_e32 v97, 31, v96
	v_pk_mul_f32 v[94:95], v[94:95], v[98:99] op_sel_hi:[1,0]
	v_pk_mul_f32 v[92:93], v[92:93], v[98:99] op_sel_hi:[1,0]
	v_pk_mul_f32 v[90:91], v[90:91], v[98:99] op_sel_hi:[1,0]
	v_max_f32_e32 v88, 0, v88
	v_max_f32_e32 v89, 0, v89
	v_lshlrev_b64 v[96:97], 14, v[96:97]
	v_max_f32_e32 v92, 0, v92
	v_max_f32_e32 v93, 0, v93
	v_pk_mul_f32 v[100:101], v[88:89], v[88:89]
	v_max_f32_e32 v88, 0, v94
	v_max_f32_e32 v90, 0, v90
	v_max_f32_e32 v89, 0, v95
	v_max_f32_e32 v91, 0, v91
	v_lshl_add_u64 v[96:97], s[6:7], 0, v[96:97]
	v_pk_mul_f32 v[92:93], v[92:93], v[92:93]
	v_pk_mul_f32 v[94:95], v[88:89], v[88:89]
	v_pk_mul_f32 v[102:103], v[90:91], v[90:91]
	v_pk_mul_f32 v[80:81], v[80:81], v[98:99] op_sel_hi:[1,0]
	v_lshl_add_u64 v[96:97], v[96:97], 0, v[142:143]
	v_cvt_pk_bf16_f32 v88, v92, v93
	v_cvt_pk_bf16_f32 v89, v94, v95
	v_cvt_pk_bf16_f32 v90, v100, v101
	v_cvt_pk_bf16_f32 v91, v102, v103
	v_pk_mul_f32 v[86:87], v[86:87], v[98:99] op_sel_hi:[1,0]
	v_pk_mul_f32 v[84:85], v[84:85], v[98:99] op_sel_hi:[1,0]
	v_pk_mul_f32 v[82:83], v[82:83], v[98:99] op_sel_hi:[1,0]
	v_max_f32_e32 v80, 0, v80
	v_max_f32_e32 v81, 0, v81
	v_lshl_add_u64 v[164:165], v[96:97], 0, v[168:169]
	ds_write_b128 v170, v[88:91]
	ds_read_b128 v[156:159], v171
	s_waitcnt lgkmcnt(3)
	global_store_dwordx4 v[166:167], v[160:163], off offset:256
	v_max_f32_e32 v84, 0, v84
	v_max_f32_e32 v85, 0, v85
	v_pk_mul_f32 v[88:89], v[80:81], v[80:81]
	v_max_f32_e32 v80, 0, v86
	v_max_f32_e32 v82, 0, v82
	v_max_f32_e32 v81, 0, v87
	v_max_f32_e32 v83, 0, v83
	v_pk_mul_f32 v[84:85], v[84:85], v[84:85]
	v_pk_mul_f32 v[86:87], v[80:81], v[80:81]
	v_pk_mul_f32 v[90:91], v[82:83], v[82:83]
	v_cvt_pk_bf16_f32 v80, v84, v85
	v_cvt_pk_bf16_f32 v81, v86, v87
	v_cvt_pk_bf16_f32 v82, v88, v89
	v_cvt_pk_bf16_f32 v83, v90, v91
	v_lshl_add_u64 v[166:167], v[96:97], 0, v[168:169]
	ds_write_b128 v170, v[80:83]
	ds_read_b128 v[160:163], v171
	s_waitcnt lgkmcnt(2)
	global_store_dwordx4 v[164:165], v[156:159], off
	s_nop 1
	v_mov_b32_e32 v82, v99
	v_or_b32_e32 v80, 48, v140
	v_pk_mul_f32 v[72:73], v[72:73], v[82:83] op_sel_hi:[1,0]
	v_ashrrev_i32_e32 v81, 31, v80
	v_pk_mul_f32 v[78:79], v[78:79], v[82:83] op_sel_hi:[1,0]
	v_pk_mul_f32 v[76:77], v[76:77], v[82:83] op_sel_hi:[1,0]
	v_pk_mul_f32 v[74:75], v[74:75], v[82:83] op_sel_hi:[1,0]
	v_max_f32_e32 v72, 0, v72
	v_max_f32_e32 v73, 0, v73
	v_lshlrev_b64 v[80:81], 14, v[80:81]
	v_max_f32_e32 v76, 0, v76
	v_max_f32_e32 v77, 0, v77
	v_pk_mul_f32 v[84:85], v[72:73], v[72:73]
	v_max_f32_e32 v72, 0, v78
	v_max_f32_e32 v74, 0, v74
	v_max_f32_e32 v73, 0, v79
	v_max_f32_e32 v75, 0, v75
	v_lshl_add_u64 v[80:81], s[6:7], 0, v[80:81]
	v_pk_mul_f32 v[76:77], v[76:77], v[76:77]
	v_pk_mul_f32 v[78:79], v[72:73], v[72:73]
	v_pk_mul_f32 v[86:87], v[74:75], v[74:75]
	v_pk_mul_f32 v[68:69], v[68:69], v[82:83] op_sel_hi:[1,0]
	v_pk_mul_f32 v[64:65], v[64:65], v[82:83] op_sel_hi:[1,0]
	v_lshl_add_u64 v[80:81], v[80:81], 0, v[142:143]
	v_cvt_pk_bf16_f32 v72, v76, v77
	v_cvt_pk_bf16_f32 v73, v78, v79
	v_cvt_pk_bf16_f32 v74, v84, v85
	v_cvt_pk_bf16_f32 v75, v86, v87
	v_pk_mul_f32 v[70:71], v[70:71], v[82:83] op_sel_hi:[1,0]
	v_max_f32_e32 v68, 0, v68
	v_max_f32_e32 v64, 0, v64
	v_max_f32_e32 v69, 0, v69
	v_max_f32_e32 v65, 0, v65
	v_lshl_add_u64 v[164:165], v[80:81], 0, v[168:169]
	ds_write_b128 v170, v[72:75]
	ds_read_b128 v[156:159], v171
	s_waitcnt lgkmcnt(2)
	global_store_dwordx4 v[166:167], v[160:163], off offset:256
	v_pk_mul_f32 v[68:69], v[68:69], v[68:69]
	v_pk_mul_f32 v[66:67], v[66:67], v[82:83] op_sel_hi:[1,0]
	v_pk_mul_f32 v[72:73], v[64:65], v[64:65]
	v_max_f32_e32 v64, 0, v70
	v_max_f32_e32 v65, 0, v71
	v_pk_mul_f32 v[70:71], v[64:65], v[64:65]
	v_cvt_pk_bf16_f32 v64, v68, v69
	ds_read2_b32 v[68:69], v148 offset0:128 offset1:144
	v_max_f32_e32 v66, 0, v66
	v_max_f32_e32 v67, 0, v67
	v_pk_mul_f32 v[74:75], v[66:67], v[66:67]
	v_cvt_pk_bf16_f32 v65, v70, v71
	s_waitcnt lgkmcnt(0)
	v_pk_mul_f32 v[60:61], v[60:61], v[68:69] op_sel_hi:[1,0]
	v_pk_mul_f32 v[56:57], v[56:57], v[68:69] op_sel_hi:[1,0]
	v_cvt_pk_bf16_f32 v66, v72, v73
	v_cvt_pk_bf16_f32 v67, v74, v75
	v_pk_mul_f32 v[62:63], v[62:63], v[68:69] op_sel_hi:[1,0]
	v_pk_mul_f32 v[58:59], v[58:59], v[68:69] op_sel_hi:[1,0]
	v_max_f32_e32 v60, 0, v60
	v_max_f32_e32 v56, 0, v56
	v_max_f32_e32 v61, 0, v61
	v_max_f32_e32 v57, 0, v57
	v_lshl_add_u64 v[166:167], v[80:81], 0, v[168:169]
	ds_write_b128 v170, v[64:67]
	ds_read_b128 v[160:163], v171
	s_waitcnt lgkmcnt(3)
	global_store_dwordx4 v[164:165], v[156:159], off
	v_pk_mul_f32 v[60:61], v[60:61], v[60:61]
	v_max_f32_e32 v58, 0, v58
	v_lshl_add_u64 v[64:65], v[138:139], 0, s[0:1]
	v_pk_mul_f32 v[66:67], v[56:57], v[56:57]
	v_max_f32_e32 v56, 0, v62
	v_max_f32_e32 v57, 0, v63
	v_max_f32_e32 v59, 0, v59
	s_mov_b32 s0, 0x200000
	v_pk_mul_f32 v[62:63], v[56:57], v[56:57]
	v_pk_mul_f32 v[70:71], v[58:59], v[58:59]
	v_cvt_pk_bf16_f32 v56, v60, v61
	v_add_co_u32_e32 v60, vcc, s0, v138
	v_pk_mul_f32 v[48:49], v[48:49], v[68:69] op_sel_hi:[1,0]
	v_cvt_pk_bf16_f32 v57, v62, v63
	v_cvt_pk_bf16_f32 v58, v66, v67
	v_cvt_pk_bf16_f32 v59, v70, v71
	v_addc_co_u32_e32 v61, vcc, 0, v139, vcc
	v_pk_mul_f32 v[54:55], v[54:55], v[68:69] op_sel_hi:[1,0]
	v_pk_mul_f32 v[52:53], v[52:53], v[68:69] op_sel_hi:[1,0]
	v_pk_mul_f32 v[50:51], v[50:51], v[68:69] op_sel_hi:[1,0]
	v_max_f32_e32 v48, 0, v48
	v_max_f32_e32 v49, 0, v49
	v_lshl_add_u64 v[164:165], v[60:61], 0, v[168:169]
	ds_write_b128 v170, v[56:59]
	ds_read_b128 v[156:159], v171
	s_waitcnt lgkmcnt(2)
; #define GAS __attribute__((address_space(1)))
; DI unsigned pk2(float lo, float hi) { f32x2 v = {lo, hi}; bf16x2_t r = __builtin_convertvector(v, bf16x2_t); return __builtin_bit_cast(unsigned, r); }
;     DI bool operator()(AccT& acc, const Unit& u, int wr, int wc, int fr, int fq) const {
;     ...
;             for (int m = 0; m < 4; ++m) { bf16* rowp = out + (size_t)(row0 + ai * HALF + m * 16) * DFF + col0; const float rsv = rs[row0 + ai * HALF + m * 16];
; #pragma unroll
;                 for (int bj = 0; bj < 2; ++bj) { f32x4 v0 = acc[ai][bj][m][0] * rsv, v1 = acc[ai][bj][m][1] * rsv;
; #pragma unroll
;                     for (int e = 0; e < 4; ++e) { const float a = fmaxf(v0[e], 0.f), b = fmaxf(v1[e], 0.f); v0[e] = a * a; v1[e] = b * b; }
;                     u32x4 w; w.x = pk2(v0[0], v0[1]); w.y = pk2(v0[2], v0[3]); w.z = pk2(v1[0], v1[1]); w.w = pk2(v1[2], v1[3]);
;                     *(GAS u32x4*)(rowp + bj * HALF) = w; } }
	global_store_dwordx4 v[166:167], v[160:163], off offset:256
	v_max_f32_e32 v52, 0, v52
	v_max_f32_e32 v53, 0, v53
	v_pk_mul_f32 v[56:57], v[48:49], v[48:49]
	v_max_f32_e32 v48, 0, v54
	v_max_f32_e32 v50, 0, v50
	v_max_f32_e32 v49, 0, v55
	v_max_f32_e32 v51, 0, v51
	v_pk_mul_f32 v[52:53], v[52:53], v[52:53]
	v_pk_mul_f32 v[54:55], v[48:49], v[48:49]
	v_pk_mul_f32 v[58:59], v[50:51], v[50:51]
	v_cvt_pk_bf16_f32 v48, v52, v53
	v_cvt_pk_bf16_f32 v49, v54, v55
	v_cvt_pk_bf16_f32 v50, v56, v57
	v_cvt_pk_bf16_f32 v51, v58, v59
	v_lshl_add_u64 v[166:167], v[64:65], 0, v[168:169]
	ds_write_b128 v170, v[48:51]
	ds_read_b128 v[160:163], v171
	s_waitcnt lgkmcnt(2)
	global_store_dwordx4 v[164:165], v[156:159], off
	s_mov_b64 s[0:1], 0x240000
	s_nop 0
	v_mov_b32_e32 v50, v69
	v_pk_mul_f32 v[44:45], v[44:45], v[50:51] op_sel_hi:[1,0]
	v_pk_mul_f32 v[40:41], v[40:41], v[50:51] op_sel_hi:[1,0]
	v_pk_mul_f32 v[46:47], v[46:47], v[50:51] op_sel_hi:[1,0]
	v_pk_mul_f32 v[42:43], v[42:43], v[50:51] op_sel_hi:[1,0]
	v_max_f32_e32 v44, 0, v44
	v_max_f32_e32 v40, 0, v40
	v_max_f32_e32 v45, 0, v45
	v_max_f32_e32 v41, 0, v41
	v_lshl_add_u64 v[48:49], v[138:139], 0, s[0:1]
	v_pk_mul_f32 v[44:45], v[44:45], v[44:45]
	v_pk_mul_f32 v[52:53], v[40:41], v[40:41]
	v_max_f32_e32 v40, 0, v46
	v_max_f32_e32 v42, 0, v42
	v_max_f32_e32 v41, 0, v47
	v_max_f32_e32 v43, 0, v43
	s_mov_b32 s0, 0x240000
	v_pk_mul_f32 v[46:47], v[40:41], v[40:41]
	v_pk_mul_f32 v[54:55], v[42:43], v[42:43]
	v_cvt_pk_bf16_f32 v40, v44, v45
	v_add_co_u32_e32 v44, vcc, s0, v138
	v_pk_mul_f32 v[36:37], v[36:37], v[50:51] op_sel_hi:[1,0]
	v_pk_mul_f32 v[32:33], v[32:33], v[50:51] op_sel_hi:[1,0]
	v_cvt_pk_bf16_f32 v41, v46, v47
	v_cvt_pk_bf16_f32 v42, v52, v53
	v_cvt_pk_bf16_f32 v43, v54, v55
	v_addc_co_u32_e32 v45, vcc, 0, v139, vcc
	v_pk_mul_f32 v[38:39], v[38:39], v[50:51] op_sel_hi:[1,0]
	v_max_f32_e32 v36, 0, v36
	v_max_f32_e32 v32, 0, v32
	v_max_f32_e32 v37, 0, v37
	v_max_f32_e32 v33, 0, v33
	v_lshl_add_u64 v[164:165], v[44:45], 0, v[168:169]
	ds_write_b128 v170, v[40:43]
	ds_read_b128 v[156:159], v171
	s_waitcnt lgkmcnt(2)
	global_store_dwordx4 v[166:167], v[160:163], off offset:256
	v_pk_mul_f32 v[36:37], v[36:37], v[36:37]
	v_pk_mul_f32 v[34:35], v[34:35], v[50:51] op_sel_hi:[1,0]
	v_pk_mul_f32 v[40:41], v[32:33], v[32:33]
	v_max_f32_e32 v32, 0, v38
	v_max_f32_e32 v33, 0, v39
	v_pk_mul_f32 v[38:39], v[32:33], v[32:33]
	v_cvt_pk_bf16_f32 v32, v36, v37
	ds_read2_b32 v[36:37], v148 offset0:160 offset1:176
	v_max_f32_e32 v34, 0, v34
	v_max_f32_e32 v35, 0, v35
	v_pk_mul_f32 v[42:43], v[34:35], v[34:35]
	v_cvt_pk_bf16_f32 v33, v38, v39
	s_waitcnt lgkmcnt(0)
	v_pk_mul_f32 v[28:29], v[28:29], v[36:37] op_sel_hi:[1,0]
	v_pk_mul_f32 v[24:25], v[24:25], v[36:37] op_sel_hi:[1,0]
	v_cvt_pk_bf16_f32 v34, v40, v41
	v_cvt_pk_bf16_f32 v35, v42, v43
	s_mov_b64 s[0:1], 0x280000
	v_pk_mul_f32 v[30:31], v[30:31], v[36:37] op_sel_hi:[1,0]
	v_pk_mul_f32 v[26:27], v[26:27], v[36:37] op_sel_hi:[1,0]
	v_max_f32_e32 v28, 0, v28
	v_max_f32_e32 v24, 0, v24
	v_max_f32_e32 v29, 0, v29
	v_max_f32_e32 v25, 0, v25
	v_lshl_add_u64 v[166:167], v[48:49], 0, v[168:169]
	ds_write_b128 v170, v[32:35]
	ds_read_b128 v[160:163], v171
	s_waitcnt lgkmcnt(3)
; #define GAS __attribute__((address_space(1)))
; DI unsigned pk2(float lo, float hi) { f32x2 v = {lo, hi}; bf16x2_t r = __builtin_convertvector(v, bf16x2_t); return __builtin_bit_cast(unsigned, r); }
;     DI bool operator()(AccT& acc, const Unit& u, int wr, int wc, int fr, int fq) const {
;     ...
;             for (int m = 0; m < 4; ++m) { bf16* rowp = out + (size_t)(row0 + ai * HALF + m * 16) * DFF + col0; const float rsv = rs[row0 + ai * HALF + m * 16];
; #pragma unroll
;                 for (int bj = 0; bj < 2; ++bj) { f32x4 v0 = acc[ai][bj][m][0] * rsv, v1 = acc[ai][bj][m][1] * rsv;
; #pragma unroll
;                     for (int e = 0; e < 4; ++e) { const float a = fmaxf(v0[e], 0.f), b = fmaxf(v1[e], 0.f); v0[e] = a * a; v1[e] = b * b; }
;                     u32x4 w; w.x = pk2(v0[0], v0[1]); w.y = pk2(v0[2], v0[3]); w.z = pk2(v1[0], v1[1]); w.w = pk2(v1[2], v1[3]);
;                     *(GAS u32x4*)(rowp + bj * HALF) = w; } }
;         return true;
	global_store_dwordx4 v[164:165], v[156:159], off
	v_pk_mul_f32 v[28:29], v[28:29], v[28:29]
	v_max_f32_e32 v26, 0, v26
	v_lshl_add_u64 v[32:33], v[138:139], 0, s[0:1]
	v_pk_mul_f32 v[34:35], v[24:25], v[24:25]
	v_max_f32_e32 v24, 0, v30
	v_max_f32_e32 v25, 0, v31
	v_max_f32_e32 v27, 0, v27
	s_mov_b32 s0, 0x280000
	v_pk_mul_f32 v[30:31], v[24:25], v[24:25]
	v_pk_mul_f32 v[38:39], v[26:27], v[26:27]
	v_cvt_pk_bf16_f32 v24, v28, v29
	v_add_co_u32_e32 v28, vcc, s0, v138
	v_pk_mul_f32 v[16:17], v[16:17], v[36:37] op_sel_hi:[1,0]
	v_cvt_pk_bf16_f32 v25, v30, v31
	v_cvt_pk_bf16_f32 v26, v34, v35
	v_cvt_pk_bf16_f32 v27, v38, v39
	v_addc_co_u32_e32 v29, vcc, 0, v139, vcc
	v_pk_mul_f32 v[22:23], v[22:23], v[36:37] op_sel_hi:[1,0]
	v_pk_mul_f32 v[20:21], v[20:21], v[36:37] op_sel_hi:[1,0]
	v_pk_mul_f32 v[18:19], v[18:19], v[36:37] op_sel_hi:[1,0]
	v_max_f32_e32 v16, 0, v16
	v_max_f32_e32 v17, 0, v17
	v_lshl_add_u64 v[164:165], v[28:29], 0, v[168:169]
	ds_write_b128 v170, v[24:27]
	ds_read_b128 v[156:159], v171
	s_waitcnt lgkmcnt(2)
	global_store_dwordx4 v[166:167], v[160:163], off offset:256
	v_max_f32_e32 v20, 0, v20
	v_max_f32_e32 v21, 0, v21
	v_pk_mul_f32 v[24:25], v[16:17], v[16:17]
	v_max_f32_e32 v16, 0, v22
	v_max_f32_e32 v18, 0, v18
	v_max_f32_e32 v17, 0, v23
	v_max_f32_e32 v19, 0, v19
	v_pk_mul_f32 v[20:21], v[20:21], v[20:21]
	v_pk_mul_f32 v[22:23], v[16:17], v[16:17]
	v_pk_mul_f32 v[26:27], v[18:19], v[18:19]
	v_cvt_pk_bf16_f32 v16, v20, v21
	v_cvt_pk_bf16_f32 v17, v22, v23
	v_cvt_pk_bf16_f32 v18, v24, v25
	v_cvt_pk_bf16_f32 v19, v26, v27
	v_lshl_add_u64 v[166:167], v[32:33], 0, v[168:169]
	ds_write_b128 v170, v[16:19]
	ds_read_b128 v[160:163], v171
	s_waitcnt lgkmcnt(2)
	global_store_dwordx4 v[164:165], v[156:159], off
	s_mov_b64 s[0:1], 0x2c0000
	s_nop 0
	v_mov_b32_e32 v18, v37
	v_pk_mul_f32 v[12:13], v[12:13], v[18:19] op_sel_hi:[1,0]
	v_pk_mul_f32 v[8:9], v[8:9], v[18:19] op_sel_hi:[1,0]
	v_pk_mul_f32 v[14:15], v[14:15], v[18:19] op_sel_hi:[1,0]
	v_pk_mul_f32 v[10:11], v[10:11], v[18:19] op_sel_hi:[1,0]
	v_max_f32_e32 v12, 0, v12
	v_max_f32_e32 v8, 0, v8
	v_max_f32_e32 v13, 0, v13
	v_max_f32_e32 v9, 0, v9
	v_lshl_add_u64 v[16:17], v[138:139], 0, s[0:1]
	v_pk_mul_f32 v[12:13], v[12:13], v[12:13]
	v_pk_mul_f32 v[20:21], v[8:9], v[8:9]
	v_max_f32_e32 v8, 0, v14
	v_max_f32_e32 v10, 0, v10
	v_max_f32_e32 v9, 0, v15
	v_max_f32_e32 v11, 0, v11
	s_mov_b32 s0, 0x2c0000
	v_pk_mul_f32 v[14:15], v[8:9], v[8:9]
	v_pk_mul_f32 v[22:23], v[10:11], v[10:11]
	v_cvt_pk_bf16_f32 v8, v12, v13
	v_add_co_u32_e32 v12, vcc, s0, v138
	v_pk_mul_f32 v[0:1], v[0:1], v[18:19] op_sel_hi:[1,0]
	v_cvt_pk_bf16_f32 v9, v14, v15
	v_cvt_pk_bf16_f32 v10, v20, v21
	v_cvt_pk_bf16_f32 v11, v22, v23
	v_addc_co_u32_e32 v13, vcc, 0, v139, vcc
	v_pk_mul_f32 v[6:7], v[6:7], v[18:19] op_sel_hi:[1,0]
	v_pk_mul_f32 v[4:5], v[4:5], v[18:19] op_sel_hi:[1,0]
	v_pk_mul_f32 v[2:3], v[2:3], v[18:19] op_sel_hi:[1,0]
	v_max_f32_e32 v0, 0, v0
	v_max_f32_e32 v1, 0, v1
	v_lshl_add_u64 v[164:165], v[12:13], 0, v[168:169]
	ds_write_b128 v170, v[8:11]
	ds_read_b128 v[156:159], v171
	s_waitcnt lgkmcnt(2)
	global_store_dwordx4 v[166:167], v[160:163], off offset:256
	v_max_f32_e32 v4, 0, v4
	v_max_f32_e32 v5, 0, v5
	v_pk_mul_f32 v[8:9], v[0:1], v[0:1]
	v_max_f32_e32 v0, 0, v6
	v_max_f32_e32 v2, 0, v2
	v_max_f32_e32 v1, 0, v7
	v_max_f32_e32 v3, 0, v3
	v_pk_mul_f32 v[4:5], v[4:5], v[4:5]
	v_pk_mul_f32 v[6:7], v[0:1], v[0:1]
	v_pk_mul_f32 v[10:11], v[2:3], v[2:3]
	v_cvt_pk_bf16_f32 v0, v4, v5
	v_cvt_pk_bf16_f32 v1, v6, v7
	v_cvt_pk_bf16_f32 v2, v8, v9
	v_cvt_pk_bf16_f32 v3, v10, v11
	s_andn2_b64 vcc, exec, s[4:5]
	s_mov_b64 s[0:1], -1
	v_lshl_add_u64 v[166:167], v[16:17], 0, v[168:169]
	ds_write_b128 v170, v[0:3]
	ds_read_b128 v[160:163], v171
	s_waitcnt lgkmcnt(2)
	global_store_dwordx4 v[164:165], v[156:159], off
	s_waitcnt lgkmcnt(0)
	global_store_dwordx4 v[166:167], v[160:163], off offset:256
	s_cbranch_vccnz .LBB0_1389
	s_andn2_b64 vcc, exec, s[2:3]
	s_cbranch_vccnz .LBB0_1388
	s_barrier
	s_branch .LBB0_1388
